# EpiYs (P4 sine-tile epilogue): all 16 loads of a 16-row step hoisted to the step top (4096-k rows loaded unmasked), one wait per step instead of 5-6; VGPRs 232->256
# speedup vs baseline: 1.0014x; 1.0004x over previous
; DEVI unsigned pk2(float lo, float hi) { f32x2 v = {lo, hi}; bf16x2_t b = __builtin_convertvector(v, bf16x2_t); return __builtin_bit_cast(unsigned, b); }
; DEVI float bflo(unsigned u) { return __uint_as_float(u << 16); }
; DEVI float bfhi(unsigned u) { return __uint_as_float(u & 0xffff0000u); }
;     template <int MT> DEVI void operator()(f32x4 (&acc)[MT][4], int row0, int col0, int fr, int fq) const {
;         const float sg = (float)(par * (1 - 2 * (fr & 1)));
;         f32x4 qt[4];
; #pragma unroll
;         for (int n = 0; n < 4; ++n) qt[n] = *(const f32x4*)(qs1024 + b * 1024 + col0 + 16 * n + 4 * fq) * sg;
; #pragma unroll
;         for (int m = 0; m < MT; ++m) {
;             __builtin_amdgcn_sched_barrier(0);
;             const int kp = row0 + 16 * m + fr, k = 2 * kp + par;
;             const float* trow = T + ((size_t)((b * 2 + par) * 1024 + kp)) * 1024 + col0 + 4 * fq;
;             bf16_t* p1 = sgf + (size_t)(b * TPB + CTX + k) * 1024 + col0 + 4 * fq;
;             bf16_t* p2 = sgf + (size_t)(b * TPB + CTX + 4096 - k) * 1024 + col0 + 4 * fq;
;             uint2 o1[4], o2[4];
; #pragma unroll
;             for (int n = 0; n < 4; ++n) {
;                 const f32x4 bb = *(const f32x4*)(bfv + col0 + 16 * n + 4 * fq);
;                 const f32x4 yc = *(const f32x4*)(trow + 16 * n);
;                 const f32x4 ys = acc[m][n] + qt[n];
;                 {
;                     const uint2 s = *(const uint2*)(p1 + 16 * n);
;                     const f32x4 v = (yc - ys) * scale + bb;
;                     o1[n].x = pk2(v[0] * bflo(s.x), v[1] * bfhi(s.x)); o1[n].y = pk2(v[2] * bflo(s.y), v[3] * bfhi(s.y));
;                 }
;                 o2[n].x = 0u; o2[n].y = 0u;
;                 if (k >= 1) {
;                     const uint2 s = *(const uint2*)(p2 + 16 * n);
;                     const f32x4 v = (yc + ys) * scale + bb;
;                     o2[n].x = pk2(v[0] * bflo(s.x), v[1] * bfhi(s.x)); o2[n].y = pk2(v[2] * bflo(s.y), v[3] * bfhi(s.y));
;                 }
.LBB0_824:
	v_lshl_or_b32 v140, v138, 6, s29
	s_ashr_i32 s29, s28, 31
	s_lshl_b64 s[0:1], s[28:29], 2
	s_add_u32 s0, s61, s0
	s_addc_u32 s1, s62, s1
	v_lshlrev_b32_e32 v184, 2, v140
	v_lshl_add_u64 v[104:105], s[0:1], 0, v[184:185]
	v_lshlrev_b32_e32 v138, 4, v177
	v_mov_b32_e32 v139, v185
	v_lshl_add_u64 v[104:105], v[104:105], 0, v[138:139]
	global_load_dwordx4 v[124:127], v[104:105], off
	global_load_dwordx4 v[120:123], v[104:105], off offset:64
	global_load_dwordx4 v[112:115], v[104:105], off offset:128
	s_nop 0
	global_load_dwordx4 v[104:107], v[104:105], off offset:192
	v_lshlrev_b32_e32 v137, 1, v137
	v_and_b32_e32 v137, 2, v137
	v_sub_u32_e32 v137, 1, v137
	v_mul_i32_i24_e32 v137, s71, v137
	v_cvt_f32_i32_e32 v190, v137
	v_and_b32_e32 v136, 0xffffff8f, v136
	v_lshl_add_u32 v173, s74, 8, v136
	s_lshl_b32 s0, s73, 11
	s_lshl_b32 s1, s71, 10
	s_or_b32 s29, s1, s0
	v_add_u32_e32 v136, s29, v173
	v_ashrrev_i32_e32 v137, 31, v136
	v_lshlrev_b64 v[136:137], 12, v[136:137]
	v_lshl_add_u64 v[136:137], s[40:41], 0, v[136:137]
	s_mul_i32 s30, s73, 0x1100
	v_lshl_or_b32 v156, v173, 1, s71
	v_lshl_add_u64 v[136:137], v[136:137], 0, v[184:185]
	s_add_i32 s28, s30, 0x100
	v_lshl_add_u64 v[168:169], v[136:137], 0, v[138:139]
	v_add_u32_e32 v136, s28, v156
	v_ashrrev_i32_e32 v137, 31, v136
	v_lshlrev_b64 v[136:137], 11, v[136:137]
	v_lshl_add_u64 v[136:137], s[54:55], 0, v[136:137]
	v_lshlrev_b32_e32 v188, 1, v140
	v_mov_b32_e32 v189, v185
	v_lshl_add_u64 v[136:137], v[136:137], 0, v[188:189]
	v_lshlrev_b32_e32 v152, 3, v177
	v_mov_b32_e32 v153, v185
	v_lshl_add_u64 v[196:197], v[136:137], 0, v[152:153]
	v_lshl_add_u64 v[136:137], s[38:39], 0, v[184:185]
	v_lshl_add_u64 v[186:187], v[136:137], 0, v[138:139]
	global_load_dwordx4 v[136:139], v[186:187], off
	global_load_dwordx4 v[140:143], v[168:169], off
	global_load_dwordx2 v[200:201], v[196:197], off
	s_addk_i32 s30, 0x1100
	v_sub_u32_e32 v154, s30, v156
	v_ashrrev_i32_e32 v155, 31, v154
	v_lshlrev_b64 v[154:155], 11, v[154:155]
	v_lshl_add_u64 v[154:155], s[54:55], 0, v[154:155]
	v_lshl_add_u64 v[154:155], v[154:155], 0, v[188:189]
	v_lshl_add_u64 v[198:199], v[154:155], 0, v[152:153]
	v_mov_b32_e32 v183, 0
	v_cmp_lt_i32_e32 vcc, 0, v156
	global_load_dwordx2 v[226:227], v[198:199], off
	global_load_dwordx4 v[232:235], v[186:187], off offset:64
	global_load_dwordx4 v[160:163], v[168:169], off offset:64
	global_load_dwordx2 v[208:209], v[196:197], off offset:32
	global_load_dwordx2 v[228:229], v[198:199], off offset:32
	global_load_dwordx4 v[236:239], v[186:187], off offset:128
	global_load_dwordx4 v[240:243], v[168:169], off offset:128
	global_load_dwordx2 v[204:205], v[196:197], off offset:64
	global_load_dwordx2 v[244:245], v[198:199], off offset:64
	global_load_dwordx4 v[246:249], v[186:187], off offset:192
	global_load_dwordx4 v[250:253], v[168:169], off offset:192
	global_load_dwordx2 v[214:215], v[196:197], off offset:96
	global_load_dwordx2 v[254:255], v[198:199], off offset:96
	s_waitcnt vmcnt(0)
	v_pk_fma_f32 v[150:151], v[190:191], v[126:127], v[150:151] op_sel_hi:[0,1,1]
	v_pk_fma_f32 v[202:203], v[190:191], v[124:125], v[148:149] op_sel_hi:[0,1,1]
	v_mov_b32_e32 v149, 0
	v_mov_b32_e32 v148, 0
	s_and_saveexec_b64 s[0:1], vcc
	s_cbranch_execz .LBB0_826
	v_pk_add_f32 v[154:155], v[202:203], v[140:141]
	v_pk_add_f32 v[152:153], v[150:151], v[142:143]
	v_pk_fma_f32 v[154:155], v[154:155], s[18:19], v[136:137] op_sel_hi:[1,0,1]
	v_pk_fma_f32 v[152:153], v[152:153], s[18:19], v[138:139] op_sel_hi:[1,0,1]
	v_lshlrev_b32_e32 v156, 16, v226
	v_and_b32_e32 v157, 0xffff0000, v226
	v_pk_mul_f32 v[154:155], v[154:155], v[156:157]
	s_nop 0
	v_cvt_pk_bf16_f32 v148, v154, v155
	v_lshlrev_b32_e32 v154, 16, v227
	v_and_b32_e32 v155, 0xffff0000, v227
	v_pk_mul_f32 v[152:153], v[152:153], v[154:155]
	s_nop 0
	v_cvt_pk_bf16_f32 v149, v152, v153
.LBB0_826:
	s_or_b64 exec, exec, s[0:1]
	v_mov_b32_e32 v191, v190
	v_mov_b32_e32 v192, v190
	v_mov_b32_e32 v193, v190
	v_pk_fma_f32 v[210:211], v[192:193], v[122:123], v[146:147]
	v_pk_fma_f32 v[212:213], v[190:191], v[120:121], v[144:145]
	v_mov_b32_e32 v189, 0
	s_and_saveexec_b64 s[0:1], vcc
	s_cbranch_execz .LBB0_828
	v_pk_add_f32 v[146:147], v[210:211], v[162:163]
	v_pk_add_f32 v[152:153], v[212:213], v[160:161]
	v_pk_fma_f32 v[146:147], v[146:147], s[18:19], v[234:235] op_sel_hi:[1,0,1]
	v_pk_fma_f32 v[152:153], v[152:153], s[18:19], v[232:233] op_sel_hi:[1,0,1]
	v_lshlrev_b32_e32 v154, 16, v228
	v_and_b32_e32 v155, 0xffff0000, v228
	v_lshlrev_b32_e32 v144, 16, v229
	v_and_b32_e32 v145, 0xffff0000, v229
	v_pk_mul_f32 v[152:153], v[152:153], v[154:155]
	v_pk_mul_f32 v[144:145], v[146:147], v[144:145]
	v_cvt_pk_bf16_f32 v189, v152, v153
	v_cvt_pk_bf16_f32 v183, v144, v145
.LBB0_828:
	s_or_b64 exec, exec, s[0:1]
	v_pk_fma_f32 v[134:135], v[192:193], v[114:115], v[134:135]
	v_pk_fma_f32 v[206:207], v[190:191], v[112:113], v[132:133]
	v_mov_b32_e32 v217, 0
	v_mov_b32_e32 v133, 0
	v_mov_b32_e32 v132, 0
	s_and_saveexec_b64 s[0:1], vcc
	s_cbranch_execz .LBB0_830
	v_pk_add_f32 v[166:167], v[206:207], v[240:241]
	v_pk_add_f32 v[164:165], v[134:135], v[242:243]
	v_pk_fma_f32 v[166:167], v[166:167], s[18:19], v[236:237] op_sel_hi:[1,0,1]
	v_pk_fma_f32 v[164:165], v[164:165], s[18:19], v[238:239] op_sel_hi:[1,0,1]
	v_lshlrev_b32_e32 v170, 16, v244
	v_and_b32_e32 v171, 0xffff0000, v244
	v_pk_mul_f32 v[166:167], v[166:167], v[170:171]
	s_nop 0
	v_cvt_pk_bf16_f32 v132, v166, v167
	v_lshlrev_b32_e32 v166, 16, v245
	v_and_b32_e32 v167, 0xffff0000, v245
	v_pk_mul_f32 v[164:165], v[164:165], v[166:167]
	s_nop 0
	v_cvt_pk_bf16_f32 v133, v164, v165
; DEVI unsigned pk2(float lo, float hi) { f32x2 v = {lo, hi}; bf16x2_t b = __builtin_convertvector(v, bf16x2_t); return __builtin_bit_cast(unsigned, b); }
; DEVI float bflo(unsigned u) { return __uint_as_float(u << 16); }
; DEVI float bfhi(unsigned u) { return __uint_as_float(u & 0xffff0000u); }
;     template <int MT> DEVI void operator()(f32x4 (&acc)[MT][4], int row0, int col0, int fr, int fq) const {
;     ...
;                 o2[n].x = 0u; o2[n].y = 0u;
;                 if (k >= 1) {
;                     const uint2 s = *(const uint2*)(p2 + 16 * n);
;                     const f32x4 v = (yc + ys) * scale + bb;
;                     o2[n].x = pk2(v[0] * bflo(s.x), v[1] * bfhi(s.x)); o2[n].y = pk2(v[2] * bflo(s.y), v[3] * bfhi(s.y));
;                 }
;             }
;             const int wo = 16 * (fq & 1) + 8 * (fq >> 1) - 4 * fq;
; #pragma unroll
;             for (int n = 0; n < 4; n += 2) {
;                 const uint4 a1 = widen16(o1[n], o1[n + 1]), a2 = widen16(o2[n], o2[n + 1]);
;                 *(uint4*)(p1 + wo + 16 * n) = a1;
;                 if (k >= 1) *(uint4*)(p2 + wo + 16 * n) = a2;
;             }
.LBB0_830:
	s_or_b64 exec, exec, s[0:1]
	s_nop 0
	s_nop 0
	v_mov_b32_e32 v194, v190
	v_mov_b32_e32 v195, v190
	v_pk_fma_f32 v[130:131], v[194:195], v[106:107], v[130:131]
	v_pk_fma_f32 v[128:129], v[190:191], v[104:105], v[128:129]
	v_mov_b32_e32 v218, 0
	s_and_saveexec_b64 s[0:1], vcc
	s_cbranch_execz .LBB0_832
	v_pk_add_f32 v[222:223], v[128:129], v[250:251]
	v_pk_add_f32 v[220:221], v[130:131], v[252:253]
	v_pk_fma_f32 v[222:223], v[222:223], s[18:19], v[246:247] op_sel_hi:[1,0,1]
	v_pk_fma_f32 v[220:221], v[220:221], s[18:19], v[248:249] op_sel_hi:[1,0,1]
	v_lshlrev_b32_e32 v224, 16, v254
	v_and_b32_e32 v225, 0xffff0000, v254
	v_pk_mul_f32 v[222:223], v[222:223], v[224:225]
	s_nop 0
	v_cvt_pk_bf16_f32 v218, v222, v223
	v_lshlrev_b32_e32 v222, 16, v255
	v_and_b32_e32 v223, 0xffff0000, v255
	v_pk_mul_f32 v[220:221], v[220:221], v[222:223]
	s_nop 0
	v_cvt_pk_bf16_f32 v217, v220, v221
.LBB0_832:
	s_or_b64 exec, exec, s[0:1]
	v_sub_f32_e32 v161, v161, v213
	v_sub_f32_e32 v160, v160, v212
	v_pk_fma_f32 v[156:157], v[160:161], s[18:19], v[232:233] op_sel_hi:[1,0,1]
	v_lshlrev_b32_e32 v160, 16, v208
	v_and_b32_e32 v161, 0xffff0000, v208
	v_sub_f32_e32 v163, v163, v211
	v_sub_f32_e32 v162, v162, v210
	v_pk_mul_f32 v[156:157], v[156:157], v[160:161]
	v_pk_fma_f32 v[158:159], v[162:163], s[18:19], v[234:235] op_sel_hi:[1,0,1]
	v_cvt_pk_bf16_f32 v160, v156, v157
	v_lshlrev_b32_e32 v156, 16, v209
	v_and_b32_e32 v157, 0xffff0000, v209
	v_pk_mul_f32 v[156:157], v[158:159], v[156:157]
	v_sub_f32_e32 v141, v141, v203
	v_sub_f32_e32 v140, v140, v202
	v_cvt_pk_bf16_f32 v161, v156, v157
	v_bfrev_b32_e32 v156, v177
	v_pk_fma_f32 v[136:137], v[140:141], s[18:19], v[136:137] op_sel_hi:[1,0,1]
	v_lshlrev_b32_e32 v140, 16, v200
	v_and_b32_e32 v141, 0xffff0000, v200
	v_lshlrev_b32_e32 v219, 2, v177
	v_lshrrev_b32_e32 v156, 27, v156
	v_sub_f32_e32 v143, v143, v151
	v_sub_f32_e32 v142, v142, v150
	v_pk_mul_f32 v[136:137], v[136:137], v[140:141]
	v_sub_u32_e32 v156, v156, v219
	v_pk_fma_f32 v[138:139], v[142:143], s[18:19], v[138:139] op_sel_hi:[1,0,1]
	v_cvt_pk_bf16_f32 v158, v136, v137
	v_lshlrev_b32_e32 v136, 16, v201
	v_and_b32_e32 v137, 0xffff0000, v201
	v_ashrrev_i32_e32 v157, 31, v156
	v_pk_mul_f32 v[136:137], v[138:139], v[136:137]
	v_lshlrev_b64 v[156:157], 1, v[156:157]
	v_cvt_pk_bf16_f32 v159, v136, v137
	v_lshl_add_u64 v[138:139], v[196:197], 0, v[156:157]
	v_lshl_add_u64 v[136:137], v[198:199], 0, v[156:157]
	v_permlane16_swap_b32_e32 v158, v160
	v_permlane16_swap_b32_e32 v159, v161
	v_permlane16_swap_b32_e32 v148, v189
	v_permlane16_swap_b32_e32 v149, v183
	global_store_dwordx4 v[138:139], v[158:161], off
	s_and_saveexec_b64 s[0:1], vcc
	s_cbranch_execz .LBB0_834
	v_mov_b32_e32 v150, v189
	v_mov_b32_e32 v151, v183
	global_store_dwordx4 v[136:137], v[148:151], off
.LBB0_834:
	s_or_b64 exec, exec, s[0:1]
	v_sub_f32_e32 v129, v251, v129
	v_sub_f32_e32 v128, v250, v128
	v_sub_f32_e32 v131, v253, v131
	v_sub_f32_e32 v130, v252, v130
	v_pk_fma_f32 v[140:141], v[130:131], s[18:19], v[248:249] op_sel_hi:[1,0,1]
	v_pk_fma_f32 v[128:129], v[128:129], s[18:19], v[246:247] op_sel_hi:[1,0,1]
	v_lshlrev_b32_e32 v130, 16, v214
	v_and_b32_e32 v131, 0xffff0000, v214
	v_pk_mul_f32 v[128:129], v[128:129], v[130:131]
	v_sub_f32_e32 v135, v243, v135
	v_cvt_pk_bf16_f32 v130, v128, v129
	v_lshlrev_b32_e32 v128, 16, v215
	v_and_b32_e32 v129, 0xffff0000, v215
	v_pk_mul_f32 v[128:129], v[140:141], v[128:129]
	v_sub_f32_e32 v134, v242, v134
	v_cvt_pk_bf16_f32 v131, v128, v129
	v_sub_f32_e32 v129, v241, v207
	v_sub_f32_e32 v128, v240, v206
	v_pk_fma_f32 v[128:129], v[128:129], s[18:19], v[236:237] op_sel_hi:[1,0,1]
	v_lshlrev_b32_e32 v140, 16, v204
	v_and_b32_e32 v141, 0xffff0000, v204
	v_pk_fma_f32 v[134:135], v[134:135], s[18:19], v[238:239] op_sel_hi:[1,0,1]
	v_pk_mul_f32 v[128:129], v[128:129], v[140:141]
	v_lshlrev_b32_e32 v140, 16, v205
	v_and_b32_e32 v141, 0xffff0000, v205
	v_pk_mul_f32 v[134:135], v[134:135], v[140:141]
	v_cvt_pk_bf16_f32 v128, v128, v129
	v_cvt_pk_bf16_f32 v129, v134, v135
	s_nop 0
	v_permlane16_swap_b32_e32 v128, v130
	v_permlane16_swap_b32_e32 v129, v131
	v_permlane16_swap_b32_e32 v132, v218
	v_permlane16_swap_b32_e32 v133, v217
	global_store_dwordx4 v[138:139], v[128:131], off offset:64
	s_and_saveexec_b64 s[0:1], vcc
	s_cbranch_execz .LBB0_836
	v_mov_b32_e32 v134, v218
	v_mov_b32_e32 v135, v217
	global_store_dwordx4 v[136:137], v[132:135], off offset:64
; DEVI unsigned pk2(float lo, float hi) { f32x2 v = {lo, hi}; bf16x2_t b = __builtin_convertvector(v, bf16x2_t); return __builtin_bit_cast(unsigned, b); }
; DEVI float bflo(unsigned u) { return __uint_as_float(u << 16); }
; DEVI float bfhi(unsigned u) { return __uint_as_float(u & 0xffff0000u); }
;     template <int MT> DEVI void operator()(f32x4 (&acc)[MT][4], int row0, int col0, int fr, int fq) const {
;     ...
;         for (int m = 0; m < MT; ++m) {
;             __builtin_amdgcn_sched_barrier(0);
;             const int kp = row0 + 16 * m + fr, k = 2 * kp + par;
;             const float* trow = T + ((size_t)((b * 2 + par) * 1024 + kp)) * 1024 + col0 + 4 * fq;
;             bf16_t* p1 = sgf + (size_t)(b * TPB + CTX + k) * 1024 + col0 + 4 * fq;
;             bf16_t* p2 = sgf + (size_t)(b * TPB + CTX + 4096 - k) * 1024 + col0 + 4 * fq;
;             uint2 o1[4], o2[4];
; #pragma unroll
;             for (int n = 0; n < 4; ++n) {
;                 const f32x4 bb = *(const f32x4*)(bfv + col0 + 16 * n + 4 * fq);
;                 const f32x4 yc = *(const f32x4*)(trow + 16 * n);
;                 const f32x4 ys = acc[m][n] + qt[n];
;                 {
;                     const uint2 s = *(const uint2*)(p1 + 16 * n);
;                     const f32x4 v = (yc - ys) * scale + bb;
;                     o1[n].x = pk2(v[0] * bflo(s.x), v[1] * bfhi(s.x)); o1[n].y = pk2(v[2] * bflo(s.y), v[3] * bfhi(s.y));
;                 }
;                 o2[n].x = 0u; o2[n].y = 0u;
;                 if (k >= 1) {
;                     const uint2 s = *(const uint2*)(p2 + 16 * n);
;                     const f32x4 v = (yc + ys) * scale + bb;
;                     o2[n].x = pk2(v[0] * bflo(s.x), v[1] * bfhi(s.x)); o2[n].y = pk2(v[2] * bflo(s.y), v[3] * bfhi(s.y));
;                 }
.LBB0_836:
	s_or_b64 exec, exec, s[0:1]
	v_pk_mul_f32 v[144:145], v[190:191], v[126:127] op_sel_hi:[0,1]
	v_pk_mul_f32 v[146:147], v[190:191], v[124:125] op_sel_hi:[0,1]
	v_or_b32_e32 v124, 16, v173
	v_lshl_or_b32 v134, v124, 1, s71
	v_add_u32_e32 v124, s29, v124
	v_ashrrev_i32_e32 v125, 31, v124
	v_lshlrev_b64 v[124:125], 12, v[124:125]
	v_lshl_add_u64 v[124:125], s[40:41], 0, v[124:125]
	v_lshl_add_u64 v[124:125], v[124:125], 0, v[184:185]
	v_lshlrev_b32_e32 v150, 2, v219
	v_mov_b32_e32 v151, v185
	v_lshl_add_u64 v[140:141], v[124:125], 0, v[150:151]
	v_add_u32_e32 v124, s28, v134
	v_ashrrev_i32_e32 v125, 31, v124
	v_lshlrev_b64 v[124:125], 11, v[124:125]
	v_lshl_add_u64 v[124:125], s[54:55], 0, v[124:125]
	v_mov_b32_e32 v189, v185
	v_lshl_add_u64 v[124:125], v[124:125], 0, v[188:189]
	v_lshlrev_b32_e32 v148, 1, v219
	v_mov_b32_e32 v149, v185
	v_lshl_add_u64 v[166:167], v[124:125], 0, v[148:149]
	global_load_dwordx4 v[124:127], v[186:187], off
	global_load_dwordx4 v[128:131], v[140:141], off
	global_load_dwordx2 v[170:171], v[166:167], off
	v_sub_u32_e32 v132, s30, v134
	v_ashrrev_i32_e32 v133, 31, v132
	v_lshlrev_b64 v[132:133], 11, v[132:133]
	v_lshl_add_u64 v[132:133], s[54:55], 0, v[132:133]
	v_lshl_add_u64 v[132:133], v[132:133], 0, v[188:189]
	v_lshl_add_u64 v[168:169], v[132:133], 0, v[148:149]
	v_mov_b32_e32 v149, 0
	v_cmp_lt_i32_e32 vcc, 0, v134
	v_pk_add_f32 v[118:119], v[118:119], v[144:145]
	v_pk_add_f32 v[196:197], v[116:117], v[146:147]
	v_mov_b32_e32 v117, 0
	v_mov_b32_e32 v116, 0
	global_load_dwordx2 v[208:209], v[168:169], off
	global_load_dwordx4 v[210:213], v[186:187], off offset:64
	global_load_dwordx4 v[220:223], v[140:141], off offset:64
	global_load_dwordx2 v[200:201], v[166:167], off offset:32
	global_load_dwordx2 v[214:215], v[168:169], off offset:32
	global_load_dwordx4 v[224:227], v[186:187], off offset:128
	global_load_dwordx4 v[232:235], v[140:141], off offset:128
	global_load_dwordx2 v[198:199], v[166:167], off offset:64
	global_load_dwordx2 v[228:229], v[168:169], off offset:64
	global_load_dwordx4 v[236:239], v[186:187], off offset:192
	global_load_dwordx4 v[240:243], v[140:141], off offset:192
	global_load_dwordx2 v[206:207], v[166:167], off offset:96
	global_load_dwordx2 v[244:245], v[168:169], off offset:96
	s_waitcnt vmcnt(0)
	s_and_saveexec_b64 s[0:1], vcc
	s_cbranch_execz .LBB0_838
	v_pk_add_f32 v[134:135], v[196:197], v[128:129]
	v_pk_add_f32 v[132:133], v[118:119], v[130:131]
	v_pk_fma_f32 v[134:135], v[134:135], s[18:19], v[124:125] op_sel_hi:[1,0,1]
	v_pk_fma_f32 v[132:133], v[132:133], s[18:19], v[126:127] op_sel_hi:[1,0,1]
	v_lshlrev_b32_e32 v136, 16, v208
	v_and_b32_e32 v137, 0xffff0000, v208
	v_pk_mul_f32 v[134:135], v[134:135], v[136:137]
	s_nop 0
	v_cvt_pk_bf16_f32 v116, v134, v135
	v_lshlrev_b32_e32 v134, 16, v209
	v_and_b32_e32 v135, 0xffff0000, v209
	v_pk_mul_f32 v[132:133], v[132:133], v[134:135]
	s_nop 0
	v_cvt_pk_bf16_f32 v117, v132, v133
.LBB0_838:
	s_or_b64 exec, exec, s[0:1]
	v_pk_mul_f32 v[152:153], v[192:193], v[122:123]
	v_pk_mul_f32 v[154:155], v[190:191], v[120:121]
	v_pk_add_f32 v[202:203], v[110:111], v[152:153]
	v_pk_add_f32 v[204:205], v[108:109], v[154:155]
	v_mov_b32_e32 v151, 0
	s_and_saveexec_b64 s[0:1], vcc
	s_cbranch_execz .LBB0_840
	v_pk_add_f32 v[110:111], v[202:203], v[222:223]
	v_pk_add_f32 v[120:121], v[204:205], v[220:221]
	v_pk_fma_f32 v[110:111], v[110:111], s[18:19], v[212:213] op_sel_hi:[1,0,1]
	v_pk_fma_f32 v[120:121], v[120:121], s[18:19], v[210:211] op_sel_hi:[1,0,1]
	v_lshlrev_b32_e32 v122, 16, v214
	v_and_b32_e32 v123, 0xffff0000, v214
	v_lshlrev_b32_e32 v108, 16, v215
	v_and_b32_e32 v109, 0xffff0000, v215
	v_pk_mul_f32 v[120:121], v[120:121], v[122:123]
	v_pk_mul_f32 v[108:109], v[110:111], v[108:109]
	v_cvt_pk_bf16_f32 v151, v120, v121
	v_cvt_pk_bf16_f32 v149, v108, v109
.LBB0_840:
	s_or_b64 exec, exec, s[0:1]
	v_pk_mul_f32 v[158:159], v[192:193], v[114:115]
	v_pk_mul_f32 v[160:161], v[190:191], v[112:113]
	v_pk_add_f32 v[102:103], v[102:103], v[158:159]
	v_pk_add_f32 v[192:193], v[100:101], v[160:161]
	v_mov_b32_e32 v177, 0
	v_mov_b32_e32 v101, 0
	v_mov_b32_e32 v100, 0
	s_and_saveexec_b64 s[0:1], vcc
	s_cbranch_execz .LBB0_842
	v_pk_add_f32 v[114:115], v[192:193], v[232:233]
	v_pk_add_f32 v[112:113], v[102:103], v[234:235]
	v_pk_fma_f32 v[114:115], v[114:115], s[18:19], v[224:225] op_sel_hi:[1,0,1]
	v_pk_fma_f32 v[112:113], v[112:113], s[18:19], v[226:227] op_sel_hi:[1,0,1]
	v_lshlrev_b32_e32 v142, 16, v228
	v_and_b32_e32 v143, 0xffff0000, v228
	v_pk_mul_f32 v[114:115], v[114:115], v[142:143]
	s_nop 0
	v_cvt_pk_bf16_f32 v100, v114, v115
	v_lshlrev_b32_e32 v114, 16, v229
	v_and_b32_e32 v115, 0xffff0000, v229
	v_pk_mul_f32 v[112:113], v[112:113], v[114:115]
	s_nop 0
	v_cvt_pk_bf16_f32 v101, v112, v113
.LBB0_842:
	s_or_b64 exec, exec, s[0:1]
	s_nop 0
	s_nop 0
	v_pk_mul_f32 v[162:163], v[194:195], v[106:107]
	v_pk_mul_f32 v[164:165], v[190:191], v[104:105]
	v_pk_add_f32 v[98:99], v[98:99], v[162:163]
	v_pk_add_f32 v[96:97], v[96:97], v[164:165]
	v_mov_b32_e32 v183, 0
	s_and_saveexec_b64 s[0:1], vcc
	s_cbranch_execz .LBB0_844
	v_pk_add_f32 v[106:107], v[98:99], v[242:243]
	v_pk_add_f32 v[190:191], v[96:97], v[240:241]
	v_pk_fma_f32 v[106:107], v[106:107], s[18:19], v[238:239] op_sel_hi:[1,0,1]
	v_pk_fma_f32 v[190:191], v[190:191], s[18:19], v[236:237] op_sel_hi:[1,0,1]
	v_lshlrev_b32_e32 v194, 16, v244
	v_and_b32_e32 v195, 0xffff0000, v244
	v_lshlrev_b32_e32 v104, 16, v245
	v_and_b32_e32 v105, 0xffff0000, v245
	v_pk_mul_f32 v[190:191], v[190:191], v[194:195]
	v_pk_mul_f32 v[104:105], v[106:107], v[104:105]
	v_cvt_pk_bf16_f32 v183, v190, v191
	v_cvt_pk_bf16_f32 v177, v104, v105
; DEVI unsigned pk2(float lo, float hi) { f32x2 v = {lo, hi}; bf16x2_t b = __builtin_convertvector(v, bf16x2_t); return __builtin_bit_cast(unsigned, b); }
; DEVI float bflo(unsigned u) { return __uint_as_float(u << 16); }
; DEVI float bfhi(unsigned u) { return __uint_as_float(u & 0xffff0000u); }
;     template <int MT> DEVI void operator()(f32x4 (&acc)[MT][4], int row0, int col0, int fr, int fq) const {
;     ...
;             const int kp = row0 + 16 * m + fr, k = 2 * kp + par;
;             const float* trow = T + ((size_t)((b * 2 + par) * 1024 + kp)) * 1024 + col0 + 4 * fq;
;             bf16_t* p1 = sgf + (size_t)(b * TPB + CTX + k) * 1024 + col0 + 4 * fq;
;             bf16_t* p2 = sgf + (size_t)(b * TPB + CTX + 4096 - k) * 1024 + col0 + 4 * fq;
;             uint2 o1[4], o2[4];
; #pragma unroll
;             for (int n = 0; n < 4; ++n) {
;                 const f32x4 bb = *(const f32x4*)(bfv + col0 + 16 * n + 4 * fq);
;                 const f32x4 yc = *(const f32x4*)(trow + 16 * n);
;                 const f32x4 ys = acc[m][n] + qt[n];
;                 {
;                     const uint2 s = *(const uint2*)(p1 + 16 * n);
;                     const f32x4 v = (yc - ys) * scale + bb;
;                     o1[n].x = pk2(v[0] * bflo(s.x), v[1] * bfhi(s.x)); o1[n].y = pk2(v[2] * bflo(s.y), v[3] * bfhi(s.y));
;                 }
;                 o2[n].x = 0u; o2[n].y = 0u;
;                 if (k >= 1) {
;                     const uint2 s = *(const uint2*)(p2 + 16 * n);
;                     const f32x4 v = (yc + ys) * scale + bb;
;                     o2[n].x = pk2(v[0] * bflo(s.x), v[1] * bfhi(s.x)); o2[n].y = pk2(v[2] * bflo(s.y), v[3] * bfhi(s.y));
;                 }
;             }
;             const int wo = 16 * (fq & 1) + 8 * (fq >> 1) - 4 * fq;
; #pragma unroll
;             for (int n = 0; n < 4; n += 2) {
;                 const uint4 a1 = widen16(o1[n], o1[n + 1]), a2 = widen16(o2[n], o2[n + 1]);
;                 *(uint4*)(p1 + wo + 16 * n) = a1;
;                 if (k >= 1) *(uint4*)(p2 + wo + 16 * n) = a2;
;             }
.LBB0_844:
	s_or_b64 exec, exec, s[0:1]
	v_sub_f32_e32 v105, v221, v205
	v_sub_f32_e32 v104, v220, v204
	v_pk_fma_f32 v[104:105], v[104:105], s[18:19], v[210:211] op_sel_hi:[1,0,1]
	v_lshlrev_b32_e32 v132, 16, v200
	v_and_b32_e32 v133, 0xffff0000, v200
	v_sub_f32_e32 v107, v223, v203
	v_sub_f32_e32 v106, v222, v202
	v_pk_mul_f32 v[104:105], v[104:105], v[132:133]
	v_pk_fma_f32 v[106:107], v[106:107], s[18:19], v[212:213] op_sel_hi:[1,0,1]
	v_cvt_pk_bf16_f32 v132, v104, v105
	v_lshlrev_b32_e32 v104, 16, v201
	v_and_b32_e32 v105, 0xffff0000, v201
	v_pk_mul_f32 v[104:105], v[106:107], v[104:105]
	v_sub_f32_e32 v107, v131, v119
	v_cvt_pk_bf16_f32 v133, v104, v105
	v_sub_f32_e32 v105, v129, v197
	v_sub_f32_e32 v104, v128, v196
	v_sub_f32_e32 v106, v130, v118
	v_pk_fma_f32 v[104:105], v[104:105], s[18:19], v[124:125] op_sel_hi:[1,0,1]
	v_lshlrev_b32_e32 v118, 16, v170
	v_and_b32_e32 v119, 0xffff0000, v170
	v_pk_mul_f32 v[104:105], v[104:105], v[118:119]
	v_pk_fma_f32 v[106:107], v[106:107], s[18:19], v[126:127] op_sel_hi:[1,0,1]
	v_cvt_pk_bf16_f32 v130, v104, v105
	v_lshlrev_b32_e32 v104, 16, v171
	v_and_b32_e32 v105, 0xffff0000, v171
	v_pk_mul_f32 v[104:105], v[106:107], v[104:105]
	v_lshl_add_u64 v[106:107], v[166:167], 0, v[156:157]
	v_cvt_pk_bf16_f32 v131, v104, v105
	v_lshl_add_u64 v[104:105], v[168:169], 0, v[156:157]
	v_permlane16_swap_b32_e32 v130, v132
	v_permlane16_swap_b32_e32 v131, v133
	v_permlane16_swap_b32_e32 v116, v151
	v_permlane16_swap_b32_e32 v117, v149
	global_store_dwordx4 v[106:107], v[130:133], off
	s_and_saveexec_b64 s[0:1], vcc
	s_cbranch_execz .LBB0_846
	v_mov_b32_e32 v118, v151
	v_mov_b32_e32 v119, v149
	global_store_dwordx4 v[104:105], v[116:119], off
.LBB0_846:
	s_or_b64 exec, exec, s[0:1]
	v_sub_f32_e32 v97, v241, v97
	v_sub_f32_e32 v96, v240, v96
	v_sub_f32_e32 v99, v243, v99
	v_sub_f32_e32 v98, v242, v98
	v_pk_fma_f32 v[114:115], v[98:99], s[18:19], v[238:239] op_sel_hi:[1,0,1]
	v_pk_fma_f32 v[96:97], v[96:97], s[18:19], v[236:237] op_sel_hi:[1,0,1]
	v_lshlrev_b32_e32 v98, 16, v206
	v_and_b32_e32 v99, 0xffff0000, v206
	v_pk_mul_f32 v[96:97], v[96:97], v[98:99]
	v_sub_f32_e32 v103, v235, v103
	v_cvt_pk_bf16_f32 v98, v96, v97
	v_lshlrev_b32_e32 v96, 16, v207
	v_and_b32_e32 v97, 0xffff0000, v207
	v_pk_mul_f32 v[96:97], v[114:115], v[96:97]
	v_sub_f32_e32 v102, v234, v102
	v_cvt_pk_bf16_f32 v99, v96, v97
	v_sub_f32_e32 v97, v233, v193
	v_sub_f32_e32 v96, v232, v192
	v_pk_fma_f32 v[96:97], v[96:97], s[18:19], v[224:225] op_sel_hi:[1,0,1]
	v_lshlrev_b32_e32 v108, 16, v198
	v_and_b32_e32 v109, 0xffff0000, v198
	v_pk_fma_f32 v[102:103], v[102:103], s[18:19], v[226:227] op_sel_hi:[1,0,1]
	v_pk_mul_f32 v[96:97], v[96:97], v[108:109]
	v_lshlrev_b32_e32 v108, 16, v199
	v_and_b32_e32 v109, 0xffff0000, v199
	v_pk_mul_f32 v[102:103], v[102:103], v[108:109]
	v_cvt_pk_bf16_f32 v96, v96, v97
	v_cvt_pk_bf16_f32 v97, v102, v103
	s_nop 0
	v_permlane16_swap_b32_e32 v96, v98
	v_permlane16_swap_b32_e32 v97, v99
	v_permlane16_swap_b32_e32 v100, v183
	v_permlane16_swap_b32_e32 v101, v177
	global_store_dwordx4 v[106:107], v[96:99], off offset:64
	s_and_saveexec_b64 s[0:1], vcc
	s_cbranch_execz .LBB0_848
	v_mov_b32_e32 v102, v183
	v_mov_b32_e32 v103, v177
	global_store_dwordx4 v[104:105], v[100:103], off offset:64
.LBB0_848:
	s_or_b64 exec, exec, s[0:1]
	v_or_b32_e32 v96, 32, v173
	v_lshl_or_b32 v106, v96, 1, s71
	v_add_u32_e32 v96, s29, v96
	v_ashrrev_i32_e32 v97, 31, v96
	v_lshlrev_b64 v[96:97], 12, v[96:97]
	v_lshl_add_u64 v[96:97], s[40:41], 0, v[96:97]
	v_lshl_add_u64 v[96:97], v[96:97], 0, v[184:185]
	v_mov_b32_e32 v151, v185
	v_lshl_add_u64 v[120:121], v[96:97], 0, v[150:151]
	v_add_u32_e32 v96, s28, v106
	v_ashrrev_i32_e32 v97, 31, v96
	v_lshlrev_b64 v[96:97], 11, v[96:97]
	v_lshl_add_u64 v[96:97], s[54:55], 0, v[96:97]
	v_mov_b32_e32 v189, v185
	v_lshl_add_u64 v[96:97], v[96:97], 0, v[188:189]
	v_mov_b32_e32 v149, v185
	v_lshl_add_u64 v[124:125], v[96:97], 0, v[148:149]
	global_load_dwordx4 v[96:99], v[186:187], off
	global_load_dwordx4 v[100:103], v[120:121], off
	global_load_dwordx2 v[128:129], v[124:125], off
	v_sub_u32_e32 v104, s30, v106
	v_ashrrev_i32_e32 v105, 31, v104
	v_lshlrev_b64 v[104:105], 11, v[104:105]
	v_lshl_add_u64 v[104:105], s[54:55], 0, v[104:105]
	v_lshl_add_u64 v[104:105], v[104:105], 0, v[188:189]
	v_lshl_add_u64 v[126:127], v[104:105], 0, v[148:149]
	v_mov_b32_e32 v149, 0
	v_cmp_lt_i32_e32 vcc, 0, v106
	v_pk_add_f32 v[94:95], v[94:95], v[144:145]
	v_pk_add_f32 v[130:131], v[92:93], v[146:147]
	v_mov_b32_e32 v93, 0
	v_mov_b32_e32 v92, 0
	global_load_dwordx2 v[206:207], v[126:127], off
	global_load_dwordx4 v[208:211], v[186:187], off offset:64
	global_load_dwordx4 v[112:115], v[120:121], off offset:64
	global_load_dwordx2 v[136:137], v[124:125], off offset:32
	global_load_dwordx2 v[212:213], v[126:127], off offset:32
	global_load_dwordx4 v[218:221], v[186:187], off offset:128
	global_load_dwordx4 v[222:225], v[120:121], off offset:128
	global_load_dwordx2 v[132:133], v[124:125], off offset:64
	global_load_dwordx2 v[214:215], v[126:127], off offset:64
	global_load_dwordx4 v[226:229], v[186:187], off offset:192
	global_load_dwordx4 v[232:235], v[120:121], off offset:192
	global_load_dwordx2 v[142:143], v[124:125], off offset:96
	global_load_dwordx2 v[236:237], v[126:127], off offset:96
	s_waitcnt vmcnt(0)
	s_and_saveexec_b64 s[0:1], vcc
	s_cbranch_execz .LBB0_850
	v_pk_add_f32 v[106:107], v[130:131], v[100:101]
	v_pk_add_f32 v[104:105], v[94:95], v[102:103]
	v_pk_fma_f32 v[106:107], v[106:107], s[18:19], v[96:97] op_sel_hi:[1,0,1]
	v_pk_fma_f32 v[104:105], v[104:105], s[18:19], v[98:99] op_sel_hi:[1,0,1]
	v_lshlrev_b32_e32 v108, 16, v206
	v_and_b32_e32 v109, 0xffff0000, v206
	v_pk_mul_f32 v[106:107], v[106:107], v[108:109]
	s_nop 0
	v_cvt_pk_bf16_f32 v92, v106, v107
	v_lshlrev_b32_e32 v106, 16, v207
	v_and_b32_e32 v107, 0xffff0000, v207
	v_pk_mul_f32 v[104:105], v[104:105], v[106:107]
	s_nop 0
	v_cvt_pk_bf16_f32 v93, v104, v105
; DEVI unsigned pk2(float lo, float hi) { f32x2 v = {lo, hi}; bf16x2_t b = __builtin_convertvector(v, bf16x2_t); return __builtin_bit_cast(unsigned, b); }
; DEVI float bflo(unsigned u) { return __uint_as_float(u << 16); }
; DEVI float bfhi(unsigned u) { return __uint_as_float(u & 0xffff0000u); }
;     template <int MT> DEVI void operator()(f32x4 (&acc)[MT][4], int row0, int col0, int fr, int fq) const {
;     ...
;                 const f32x4 ys = acc[m][n] + qt[n];
;                 {
;                     const uint2 s = *(const uint2*)(p1 + 16 * n);
;                     const f32x4 v = (yc - ys) * scale + bb;
;                     o1[n].x = pk2(v[0] * bflo(s.x), v[1] * bfhi(s.x)); o1[n].y = pk2(v[2] * bflo(s.y), v[3] * bfhi(s.y));
;                 }
;                 o2[n].x = 0u; o2[n].y = 0u;
;                 if (k >= 1) {
;                     const uint2 s = *(const uint2*)(p2 + 16 * n);
;                     const f32x4 v = (yc + ys) * scale + bb;
;                     o2[n].x = pk2(v[0] * bflo(s.x), v[1] * bfhi(s.x)); o2[n].y = pk2(v[2] * bflo(s.y), v[3] * bfhi(s.y));
;                 }
;             }
;             const int wo = 16 * (fq & 1) + 8 * (fq >> 1) - 4 * fq;
; #pragma unroll
;             for (int n = 0; n < 4; n += 2) {
;                 const uint4 a1 = widen16(o1[n], o1[n + 1]), a2 = widen16(o2[n], o2[n + 1]);
;                 *(uint4*)(p1 + wo + 16 * n) = a1;
;                 if (k >= 1) *(uint4*)(p2 + wo + 16 * n) = a2;
;             }
.LBB0_850:
	s_or_b64 exec, exec, s[0:1]
	v_pk_add_f32 v[138:139], v[90:91], v[152:153]
	v_pk_add_f32 v[140:141], v[88:89], v[154:155]
	v_mov_b32_e32 v151, 0
	s_and_saveexec_b64 s[0:1], vcc
	s_cbranch_execz .LBB0_852
	v_pk_add_f32 v[90:91], v[138:139], v[114:115]
	v_pk_add_f32 v[104:105], v[140:141], v[112:113]
	v_pk_fma_f32 v[90:91], v[90:91], s[18:19], v[210:211] op_sel_hi:[1,0,1]
	v_pk_fma_f32 v[104:105], v[104:105], s[18:19], v[208:209] op_sel_hi:[1,0,1]
	v_lshlrev_b32_e32 v106, 16, v212
	v_and_b32_e32 v107, 0xffff0000, v212
	v_lshlrev_b32_e32 v88, 16, v213
	v_and_b32_e32 v89, 0xffff0000, v213
	v_pk_mul_f32 v[104:105], v[104:105], v[106:107]
	v_pk_mul_f32 v[88:89], v[90:91], v[88:89]
	v_cvt_pk_bf16_f32 v151, v104, v105
	v_cvt_pk_bf16_f32 v149, v88, v89
.LBB0_852:
	s_or_b64 exec, exec, s[0:1]
	v_pk_add_f32 v[86:87], v[86:87], v[158:159]
	v_pk_add_f32 v[134:135], v[84:85], v[160:161]
	v_mov_b32_e32 v166, 0
	v_mov_b32_e32 v85, 0
	v_mov_b32_e32 v84, 0
	s_and_saveexec_b64 s[0:1], vcc
	s_cbranch_execz .LBB0_854
	v_pk_add_f32 v[118:119], v[134:135], v[222:223]
	v_pk_add_f32 v[116:117], v[86:87], v[224:225]
	v_pk_fma_f32 v[118:119], v[118:119], s[18:19], v[218:219] op_sel_hi:[1,0,1]
	v_pk_fma_f32 v[116:117], v[116:117], s[18:19], v[220:221] op_sel_hi:[1,0,1]
	v_lshlrev_b32_e32 v122, 16, v214
	v_and_b32_e32 v123, 0xffff0000, v214
	v_pk_mul_f32 v[118:119], v[118:119], v[122:123]
	s_nop 0
	v_cvt_pk_bf16_f32 v84, v118, v119
	v_lshlrev_b32_e32 v118, 16, v215
	v_and_b32_e32 v119, 0xffff0000, v215
	v_pk_mul_f32 v[116:117], v[116:117], v[118:119]
	s_nop 0
	v_cvt_pk_bf16_f32 v85, v116, v117
.LBB0_854:
	s_or_b64 exec, exec, s[0:1]
	s_nop 0
	s_nop 0
	v_pk_add_f32 v[82:83], v[82:83], v[162:163]
	v_pk_add_f32 v[80:81], v[80:81], v[164:165]
	v_mov_b32_e32 v167, 0
	s_and_saveexec_b64 s[0:1], vcc
	s_cbranch_execz .LBB0_856
	v_pk_add_f32 v[166:167], v[82:83], v[234:235]
	v_pk_add_f32 v[170:171], v[80:81], v[232:233]
	v_pk_fma_f32 v[190:191], v[166:167], s[18:19], v[228:229] op_sel_hi:[1,0,1]
	v_pk_fma_f32 v[166:167], v[170:171], s[18:19], v[226:227] op_sel_hi:[1,0,1]
	v_lshlrev_b32_e32 v170, 16, v236
	v_and_b32_e32 v171, 0xffff0000, v236
	v_lshlrev_b32_e32 v168, 16, v237
	v_and_b32_e32 v169, 0xffff0000, v237
	v_pk_mul_f32 v[166:167], v[166:167], v[170:171]
	v_pk_mul_f32 v[168:169], v[190:191], v[168:169]
	v_cvt_pk_bf16_f32 v167, v166, v167
	v_cvt_pk_bf16_f32 v166, v168, v169
.LBB0_856:
	s_or_b64 exec, exec, s[0:1]
	v_sub_f32_e32 v113, v113, v141
	v_sub_f32_e32 v112, v112, v140
	v_sub_f32_e32 v115, v115, v139
	v_sub_f32_e32 v114, v114, v138
	v_pk_fma_f32 v[114:115], v[114:115], s[18:19], v[210:211] op_sel_hi:[1,0,1]
	v_pk_fma_f32 v[108:109], v[112:113], s[18:19], v[208:209] op_sel_hi:[1,0,1]
	v_lshlrev_b32_e32 v110, 16, v136
	v_and_b32_e32 v111, 0xffff0000, v136
	v_pk_mul_f32 v[108:109], v[108:109], v[110:111]
	v_sub_f32_e32 v101, v101, v131
	v_sub_f32_e32 v100, v100, v130
	v_sub_f32_e32 v95, v103, v95
	v_sub_f32_e32 v94, v102, v94
	v_cvt_pk_bf16_f32 v110, v108, v109
	v_lshlrev_b32_e32 v108, 16, v137
	v_and_b32_e32 v109, 0xffff0000, v137
	v_pk_fma_f32 v[94:95], v[94:95], s[18:19], v[98:99] op_sel_hi:[1,0,1]
	v_pk_fma_f32 v[96:97], v[100:101], s[18:19], v[96:97] op_sel_hi:[1,0,1]
	v_lshlrev_b32_e32 v98, 16, v128
	v_and_b32_e32 v99, 0xffff0000, v128
	v_pk_mul_f32 v[108:109], v[114:115], v[108:109]
	v_pk_mul_f32 v[96:97], v[96:97], v[98:99]
	v_cvt_pk_bf16_f32 v111, v108, v109
	v_cvt_pk_bf16_f32 v108, v96, v97
	v_lshlrev_b32_e32 v96, 16, v129
	v_and_b32_e32 v97, 0xffff0000, v129
	v_pk_mul_f32 v[94:95], v[94:95], v[96:97]
	v_lshl_add_u64 v[98:99], v[124:125], 0, v[156:157]
	v_cvt_pk_bf16_f32 v109, v94, v95
	v_lshl_add_u64 v[96:97], v[126:127], 0, v[156:157]
	v_permlane16_swap_b32_e32 v108, v110
	v_permlane16_swap_b32_e32 v109, v111
	v_permlane16_swap_b32_e32 v92, v151
	v_permlane16_swap_b32_e32 v93, v149
	global_store_dwordx4 v[98:99], v[108:111], off
	s_and_saveexec_b64 s[0:1], vcc
	s_cbranch_execz .LBB0_858
	v_mov_b32_e32 v94, v151
	v_mov_b32_e32 v95, v149
	global_store_dwordx4 v[96:97], v[92:95], off
.LBB0_858:
	s_or_b64 exec, exec, s[0:1]
	v_sub_f32_e32 v81, v233, v81
	v_sub_f32_e32 v80, v232, v80
	v_sub_f32_e32 v83, v235, v83
	v_sub_f32_e32 v82, v234, v82
	v_pk_fma_f32 v[92:93], v[82:83], s[18:19], v[228:229] op_sel_hi:[1,0,1]
	v_pk_fma_f32 v[80:81], v[80:81], s[18:19], v[226:227] op_sel_hi:[1,0,1]
	v_lshlrev_b32_e32 v82, 16, v142
	v_and_b32_e32 v83, 0xffff0000, v142
	v_pk_mul_f32 v[80:81], v[80:81], v[82:83]
	v_sub_f32_e32 v87, v225, v87
	v_cvt_pk_bf16_f32 v82, v80, v81
	v_lshlrev_b32_e32 v80, 16, v143
	v_and_b32_e32 v81, 0xffff0000, v143
	v_pk_mul_f32 v[80:81], v[92:93], v[80:81]
	v_sub_f32_e32 v86, v224, v86
	v_cvt_pk_bf16_f32 v83, v80, v81
	v_sub_f32_e32 v81, v223, v135
	v_sub_f32_e32 v80, v222, v134
	v_pk_fma_f32 v[80:81], v[80:81], s[18:19], v[218:219] op_sel_hi:[1,0,1]
	v_lshlrev_b32_e32 v88, 16, v132
	v_and_b32_e32 v89, 0xffff0000, v132
	v_pk_fma_f32 v[86:87], v[86:87], s[18:19], v[220:221] op_sel_hi:[1,0,1]
	v_pk_mul_f32 v[80:81], v[80:81], v[88:89]
	v_lshlrev_b32_e32 v88, 16, v133
	v_and_b32_e32 v89, 0xffff0000, v133
	v_pk_mul_f32 v[86:87], v[86:87], v[88:89]
	v_cvt_pk_bf16_f32 v80, v80, v81
	v_cvt_pk_bf16_f32 v81, v86, v87
	s_nop 0
	v_permlane16_swap_b32_e32 v80, v82
	v_permlane16_swap_b32_e32 v81, v83
	v_permlane16_swap_b32_e32 v84, v167
	v_permlane16_swap_b32_e32 v85, v166
	global_store_dwordx4 v[98:99], v[80:83], off offset:64
	s_and_saveexec_b64 s[0:1], vcc
	s_cbranch_execz .LBB0_860
	v_mov_b32_e32 v86, v167
	v_mov_b32_e32 v87, v166
	global_store_dwordx4 v[96:97], v[84:87], off offset:64
; DEVI unsigned pk2(float lo, float hi) { f32x2 v = {lo, hi}; bf16x2_t b = __builtin_convertvector(v, bf16x2_t); return __builtin_bit_cast(unsigned, b); }
; DEVI float bflo(unsigned u) { return __uint_as_float(u << 16); }
; DEVI float bfhi(unsigned u) { return __uint_as_float(u & 0xffff0000u); }
;     template <int MT> DEVI void operator()(f32x4 (&acc)[MT][4], int row0, int col0, int fr, int fq) const {
;     ...
;             const int kp = row0 + 16 * m + fr, k = 2 * kp + par;
;             const float* trow = T + ((size_t)((b * 2 + par) * 1024 + kp)) * 1024 + col0 + 4 * fq;
;             bf16_t* p1 = sgf + (size_t)(b * TPB + CTX + k) * 1024 + col0 + 4 * fq;
;             bf16_t* p2 = sgf + (size_t)(b * TPB + CTX + 4096 - k) * 1024 + col0 + 4 * fq;
;             uint2 o1[4], o2[4];
; #pragma unroll
;             for (int n = 0; n < 4; ++n) {
;                 const f32x4 bb = *(const f32x4*)(bfv + col0 + 16 * n + 4 * fq);
;                 const f32x4 yc = *(const f32x4*)(trow + 16 * n);
;                 const f32x4 ys = acc[m][n] + qt[n];
;                 {
;                     const uint2 s = *(const uint2*)(p1 + 16 * n);
;                     const f32x4 v = (yc - ys) * scale + bb;
;                     o1[n].x = pk2(v[0] * bflo(s.x), v[1] * bfhi(s.x)); o1[n].y = pk2(v[2] * bflo(s.y), v[3] * bfhi(s.y));
;                 }
;                 o2[n].x = 0u; o2[n].y = 0u;
;                 if (k >= 1) {
;                     const uint2 s = *(const uint2*)(p2 + 16 * n);
;                     const f32x4 v = (yc + ys) * scale + bb;
;                     o2[n].x = pk2(v[0] * bflo(s.x), v[1] * bfhi(s.x)); o2[n].y = pk2(v[2] * bflo(s.y), v[3] * bfhi(s.y));
;                 }
.LBB0_860:
	s_or_b64 exec, exec, s[0:1]
	v_or_b32_e32 v80, 48, v173
	v_lshl_or_b32 v90, v80, 1, s71
	v_add_u32_e32 v80, s29, v80
	v_ashrrev_i32_e32 v81, 31, v80
	v_lshlrev_b64 v[80:81], 12, v[80:81]
	v_lshl_add_u64 v[80:81], s[40:41], 0, v[80:81]
	v_lshl_add_u64 v[80:81], v[80:81], 0, v[184:185]
	v_mov_b32_e32 v151, v185
	v_lshl_add_u64 v[104:105], v[80:81], 0, v[150:151]
	v_add_u32_e32 v80, s28, v90
	v_ashrrev_i32_e32 v81, 31, v80
	v_lshlrev_b64 v[80:81], 11, v[80:81]
	v_lshl_add_u64 v[80:81], s[54:55], 0, v[80:81]
	v_mov_b32_e32 v189, v185
	v_lshl_add_u64 v[80:81], v[80:81], 0, v[188:189]
	v_mov_b32_e32 v149, v185
	v_lshl_add_u64 v[108:109], v[80:81], 0, v[148:149]
	global_load_dwordx4 v[80:83], v[186:187], off
	global_load_dwordx4 v[84:87], v[104:105], off
	global_load_dwordx2 v[112:113], v[108:109], off
	v_sub_u32_e32 v88, s30, v90
	v_ashrrev_i32_e32 v89, 31, v88
	v_lshlrev_b64 v[88:89], 11, v[88:89]
	v_lshl_add_u64 v[88:89], s[54:55], 0, v[88:89]
	v_lshl_add_u64 v[88:89], v[88:89], 0, v[188:189]
	v_lshl_add_u64 v[110:111], v[88:89], 0, v[148:149]
	v_mov_b32_e32 v128, 0
	v_cmp_lt_i32_e32 vcc, 0, v90
	v_pk_add_f32 v[78:79], v[78:79], v[144:145]
	v_pk_add_f32 v[114:115], v[76:77], v[146:147]
	v_mov_b32_e32 v77, 0
	v_mov_b32_e32 v76, 0
	global_load_dwordx2 v[138:139], v[110:111], off
	global_load_dwordx4 v[140:143], v[186:187], off offset:64
	global_load_dwordx4 v[96:99], v[104:105], off offset:64
	global_load_dwordx2 v[120:121], v[108:109], off offset:32
	global_load_dwordx2 v[206:207], v[110:111], off offset:32
	global_load_dwordx4 v[208:211], v[186:187], off offset:128
	global_load_dwordx4 v[212:215], v[104:105], off offset:128
	global_load_dwordx2 v[116:117], v[108:109], off offset:64
	global_load_dwordx2 v[218:219], v[110:111], off offset:64
	global_load_dwordx4 v[220:223], v[186:187], off offset:192
	global_load_dwordx4 v[224:227], v[104:105], off offset:192
	global_load_dwordx2 v[126:127], v[108:109], off offset:96
	global_load_dwordx2 v[228:229], v[110:111], off offset:96
	s_waitcnt vmcnt(0)
	s_and_saveexec_b64 s[0:1], vcc
	s_cbranch_execz .LBB0_862
	v_pk_add_f32 v[90:91], v[114:115], v[84:85]
	v_pk_add_f32 v[88:89], v[78:79], v[86:87]
	v_pk_fma_f32 v[90:91], v[90:91], s[18:19], v[80:81] op_sel_hi:[1,0,1]
	v_pk_fma_f32 v[88:89], v[88:89], s[18:19], v[82:83] op_sel_hi:[1,0,1]
	v_lshlrev_b32_e32 v92, 16, v138
	v_and_b32_e32 v93, 0xffff0000, v138
	v_pk_mul_f32 v[90:91], v[90:91], v[92:93]
	s_nop 0
	v_cvt_pk_bf16_f32 v76, v90, v91
	v_lshlrev_b32_e32 v90, 16, v139
	v_and_b32_e32 v91, 0xffff0000, v139
	v_pk_mul_f32 v[88:89], v[88:89], v[90:91]
	s_nop 0
	v_cvt_pk_bf16_f32 v77, v88, v89
.LBB0_862:
	s_or_b64 exec, exec, s[0:1]
	v_pk_add_f32 v[122:123], v[74:75], v[152:153]
	v_pk_add_f32 v[124:125], v[72:73], v[154:155]
	v_mov_b32_e32 v129, 0
	s_and_saveexec_b64 s[0:1], vcc
	s_cbranch_execz .LBB0_864
	v_pk_add_f32 v[74:75], v[122:123], v[98:99]
	v_pk_add_f32 v[88:89], v[124:125], v[96:97]
	v_pk_fma_f32 v[74:75], v[74:75], s[18:19], v[142:143] op_sel_hi:[1,0,1]
	v_pk_fma_f32 v[88:89], v[88:89], s[18:19], v[140:141] op_sel_hi:[1,0,1]
	v_lshlrev_b32_e32 v90, 16, v206
	v_and_b32_e32 v91, 0xffff0000, v206
	v_lshlrev_b32_e32 v72, 16, v207
	v_and_b32_e32 v73, 0xffff0000, v207
	v_pk_mul_f32 v[88:89], v[88:89], v[90:91]
	v_pk_mul_f32 v[72:73], v[74:75], v[72:73]
	v_cvt_pk_bf16_f32 v129, v88, v89
	v_cvt_pk_bf16_f32 v128, v72, v73
.LBB0_864:
	s_or_b64 exec, exec, s[0:1]
	v_pk_add_f32 v[70:71], v[70:71], v[158:159]
	v_pk_add_f32 v[118:119], v[68:69], v[160:161]
	v_mov_b32_e32 v130, 0
	v_mov_b32_e32 v69, 0
	v_mov_b32_e32 v68, 0
	s_and_saveexec_b64 s[0:1], vcc
	s_cbranch_execz .LBB0_866
	v_pk_add_f32 v[102:103], v[118:119], v[212:213]
	v_pk_add_f32 v[100:101], v[70:71], v[214:215]
	v_pk_fma_f32 v[102:103], v[102:103], s[18:19], v[208:209] op_sel_hi:[1,0,1]
	v_pk_fma_f32 v[100:101], v[100:101], s[18:19], v[210:211] op_sel_hi:[1,0,1]
	v_lshlrev_b32_e32 v106, 16, v218
	v_and_b32_e32 v107, 0xffff0000, v218
	v_pk_mul_f32 v[102:103], v[102:103], v[106:107]
	s_nop 0
	v_cvt_pk_bf16_f32 v68, v102, v103
	v_lshlrev_b32_e32 v102, 16, v219
	v_and_b32_e32 v103, 0xffff0000, v219
	v_pk_mul_f32 v[100:101], v[100:101], v[102:103]
	s_nop 0
	v_cvt_pk_bf16_f32 v69, v100, v101
.LBB0_866:
	s_or_b64 exec, exec, s[0:1]
	s_nop 0
	s_nop 0
	v_pk_add_f32 v[66:67], v[66:67], v[162:163]
	v_pk_add_f32 v[64:65], v[64:65], v[164:165]
	v_mov_b32_e32 v131, 0
	s_and_saveexec_b64 s[0:1], vcc
	s_cbranch_execz .LBB0_868
	v_pk_add_f32 v[130:131], v[66:67], v[226:227]
	v_pk_add_f32 v[134:135], v[64:65], v[224:225]
	v_pk_fma_f32 v[136:137], v[130:131], s[18:19], v[222:223] op_sel_hi:[1,0,1]
	v_pk_fma_f32 v[130:131], v[134:135], s[18:19], v[220:221] op_sel_hi:[1,0,1]
	v_lshlrev_b32_e32 v134, 16, v228
	v_and_b32_e32 v135, 0xffff0000, v228
	v_lshlrev_b32_e32 v132, 16, v229
	v_and_b32_e32 v133, 0xffff0000, v229
	v_pk_mul_f32 v[130:131], v[130:131], v[134:135]
	v_pk_mul_f32 v[132:133], v[136:137], v[132:133]
	v_cvt_pk_bf16_f32 v131, v130, v131
	v_cvt_pk_bf16_f32 v130, v132, v133
; DEVI unsigned pk2(float lo, float hi) { f32x2 v = {lo, hi}; bf16x2_t b = __builtin_convertvector(v, bf16x2_t); return __builtin_bit_cast(unsigned, b); }
; DEVI float bflo(unsigned u) { return __uint_as_float(u << 16); }
; DEVI float bfhi(unsigned u) { return __uint_as_float(u & 0xffff0000u); }
;     template <int MT> DEVI void operator()(f32x4 (&acc)[MT][4], int row0, int col0, int fr, int fq) const {
;     ...
;             const int kp = row0 + 16 * m + fr, k = 2 * kp + par;
;             const float* trow = T + ((size_t)((b * 2 + par) * 1024 + kp)) * 1024 + col0 + 4 * fq;
;             bf16_t* p1 = sgf + (size_t)(b * TPB + CTX + k) * 1024 + col0 + 4 * fq;
;             bf16_t* p2 = sgf + (size_t)(b * TPB + CTX + 4096 - k) * 1024 + col0 + 4 * fq;
;             uint2 o1[4], o2[4];
; #pragma unroll
;             for (int n = 0; n < 4; ++n) {
;                 const f32x4 bb = *(const f32x4*)(bfv + col0 + 16 * n + 4 * fq);
;                 const f32x4 yc = *(const f32x4*)(trow + 16 * n);
;                 const f32x4 ys = acc[m][n] + qt[n];
;                 {
;                     const uint2 s = *(const uint2*)(p1 + 16 * n);
;                     const f32x4 v = (yc - ys) * scale + bb;
;                     o1[n].x = pk2(v[0] * bflo(s.x), v[1] * bfhi(s.x)); o1[n].y = pk2(v[2] * bflo(s.y), v[3] * bfhi(s.y));
;                 }
;                 o2[n].x = 0u; o2[n].y = 0u;
;                 if (k >= 1) {
;                     const uint2 s = *(const uint2*)(p2 + 16 * n);
;                     const f32x4 v = (yc + ys) * scale + bb;
;                     o2[n].x = pk2(v[0] * bflo(s.x), v[1] * bfhi(s.x)); o2[n].y = pk2(v[2] * bflo(s.y), v[3] * bfhi(s.y));
;                 }
;             }
;             const int wo = 16 * (fq & 1) + 8 * (fq >> 1) - 4 * fq;
; #pragma unroll
;             for (int n = 0; n < 4; n += 2) {
;                 const uint4 a1 = widen16(o1[n], o1[n + 1]), a2 = widen16(o2[n], o2[n + 1]);
;                 *(uint4*)(p1 + wo + 16 * n) = a1;
;                 if (k >= 1) *(uint4*)(p2 + wo + 16 * n) = a2;
;             }
.LBB0_868:
	s_or_b64 exec, exec, s[0:1]
	v_sub_f32_e32 v97, v97, v125
	v_sub_f32_e32 v96, v96, v124
	v_sub_f32_e32 v99, v99, v123
	v_sub_f32_e32 v98, v98, v122
	v_pk_fma_f32 v[98:99], v[98:99], s[18:19], v[142:143] op_sel_hi:[1,0,1]
	v_pk_fma_f32 v[92:93], v[96:97], s[18:19], v[140:141] op_sel_hi:[1,0,1]
	v_lshlrev_b32_e32 v94, 16, v120
	v_and_b32_e32 v95, 0xffff0000, v120
	v_pk_mul_f32 v[92:93], v[92:93], v[94:95]
	v_sub_f32_e32 v85, v85, v115
	v_sub_f32_e32 v84, v84, v114
	v_sub_f32_e32 v79, v87, v79
	v_sub_f32_e32 v78, v86, v78
	v_cvt_pk_bf16_f32 v94, v92, v93
	v_lshlrev_b32_e32 v92, 16, v121
	v_and_b32_e32 v93, 0xffff0000, v121
	v_pk_fma_f32 v[78:79], v[78:79], s[18:19], v[82:83] op_sel_hi:[1,0,1]
	v_pk_fma_f32 v[80:81], v[84:85], s[18:19], v[80:81] op_sel_hi:[1,0,1]
	v_lshlrev_b32_e32 v82, 16, v112
	v_and_b32_e32 v83, 0xffff0000, v112
	v_pk_mul_f32 v[92:93], v[98:99], v[92:93]
	v_pk_mul_f32 v[80:81], v[80:81], v[82:83]
	v_cvt_pk_bf16_f32 v95, v92, v93
	v_cvt_pk_bf16_f32 v92, v80, v81
	v_lshlrev_b32_e32 v80, 16, v113
	v_and_b32_e32 v81, 0xffff0000, v113
	v_pk_mul_f32 v[78:79], v[78:79], v[80:81]
	v_lshl_add_u64 v[82:83], v[108:109], 0, v[156:157]
	v_cvt_pk_bf16_f32 v93, v78, v79
	v_lshl_add_u64 v[80:81], v[110:111], 0, v[156:157]
	v_permlane16_swap_b32_e32 v92, v94
	v_permlane16_swap_b32_e32 v93, v95
	v_permlane16_swap_b32_e32 v76, v129
	v_permlane16_swap_b32_e32 v77, v128
	global_store_dwordx4 v[82:83], v[92:95], off
	s_and_saveexec_b64 s[0:1], vcc
	s_cbranch_execz .LBB0_870
	v_mov_b32_e32 v78, v129
	v_mov_b32_e32 v79, v128
	global_store_dwordx4 v[80:81], v[76:79], off
.LBB0_870:
	s_or_b64 exec, exec, s[0:1]
	v_sub_f32_e32 v65, v225, v65
	v_sub_f32_e32 v64, v224, v64
	v_sub_f32_e32 v67, v227, v67
	v_sub_f32_e32 v66, v226, v66
	v_pk_fma_f32 v[76:77], v[66:67], s[18:19], v[222:223] op_sel_hi:[1,0,1]
	v_pk_fma_f32 v[64:65], v[64:65], s[18:19], v[220:221] op_sel_hi:[1,0,1]
	v_lshlrev_b32_e32 v66, 16, v126
	v_and_b32_e32 v67, 0xffff0000, v126
	v_pk_mul_f32 v[64:65], v[64:65], v[66:67]
	v_sub_f32_e32 v71, v215, v71
	v_cvt_pk_bf16_f32 v66, v64, v65
	v_lshlrev_b32_e32 v64, 16, v127
	v_and_b32_e32 v65, 0xffff0000, v127
	v_pk_mul_f32 v[64:65], v[76:77], v[64:65]
	v_sub_f32_e32 v70, v214, v70
	v_cvt_pk_bf16_f32 v67, v64, v65
	v_sub_f32_e32 v65, v213, v119
	v_sub_f32_e32 v64, v212, v118
	v_pk_fma_f32 v[64:65], v[64:65], s[18:19], v[208:209] op_sel_hi:[1,0,1]
	v_lshlrev_b32_e32 v72, 16, v116
	v_and_b32_e32 v73, 0xffff0000, v116
	v_pk_fma_f32 v[70:71], v[70:71], s[18:19], v[210:211] op_sel_hi:[1,0,1]
	v_pk_mul_f32 v[64:65], v[64:65], v[72:73]
	v_lshlrev_b32_e32 v72, 16, v117
	v_and_b32_e32 v73, 0xffff0000, v117
	v_pk_mul_f32 v[70:71], v[70:71], v[72:73]
	v_cvt_pk_bf16_f32 v64, v64, v65
	v_cvt_pk_bf16_f32 v65, v70, v71
	s_nop 0
	v_permlane16_swap_b32_e32 v64, v66
	v_permlane16_swap_b32_e32 v65, v67
	v_permlane16_swap_b32_e32 v68, v131
	v_permlane16_swap_b32_e32 v69, v130
	global_store_dwordx4 v[82:83], v[64:67], off offset:64
	s_and_saveexec_b64 s[0:1], vcc
	s_cbranch_execz .LBB0_872
	v_mov_b32_e32 v70, v131
	v_mov_b32_e32 v71, v130
	global_store_dwordx4 v[80:81], v[68:71], off offset:64
.LBB0_872:
	s_or_b64 exec, exec, s[0:1]
	v_or_b32_e32 v64, 64, v173
	v_lshl_or_b32 v74, v64, 1, s71
	v_add_u32_e32 v64, s29, v64
	v_ashrrev_i32_e32 v65, 31, v64
	v_lshlrev_b64 v[64:65], 12, v[64:65]
	v_lshl_add_u64 v[64:65], s[40:41], 0, v[64:65]
	v_lshl_add_u64 v[64:65], v[64:65], 0, v[184:185]
	v_mov_b32_e32 v151, v185
	v_lshl_add_u64 v[88:89], v[64:65], 0, v[150:151]
	v_add_u32_e32 v64, s28, v74
	v_ashrrev_i32_e32 v65, 31, v64
	v_lshlrev_b64 v[64:65], 11, v[64:65]
	v_lshl_add_u64 v[64:65], s[54:55], 0, v[64:65]
	v_mov_b32_e32 v189, v185
	v_lshl_add_u64 v[64:65], v[64:65], 0, v[188:189]
	v_mov_b32_e32 v149, v185
	v_lshl_add_u64 v[92:93], v[64:65], 0, v[148:149]
	global_load_dwordx4 v[64:67], v[186:187], off
	global_load_dwordx4 v[68:71], v[88:89], off
	global_load_dwordx2 v[96:97], v[92:93], off
	v_sub_u32_e32 v72, s30, v74
	v_ashrrev_i32_e32 v73, 31, v72
	v_lshlrev_b64 v[72:73], 11, v[72:73]
	v_lshl_add_u64 v[72:73], s[54:55], 0, v[72:73]
	v_lshl_add_u64 v[72:73], v[72:73], 0, v[188:189]
	v_lshl_add_u64 v[94:95], v[72:73], 0, v[148:149]
	v_mov_b32_e32 v112, 0
	v_cmp_lt_i32_e32 vcc, 0, v74
	v_pk_add_f32 v[62:63], v[62:63], v[144:145]
	v_pk_add_f32 v[98:99], v[60:61], v[146:147]
	v_mov_b32_e32 v61, 0
	v_mov_b32_e32 v60, 0
	global_load_dwordx2 v[122:123], v[94:95], off
	global_load_dwordx4 v[124:127], v[186:187], off offset:64
	global_load_dwordx4 v[80:83], v[88:89], off offset:64
	global_load_dwordx2 v[104:105], v[92:93], off offset:32
	global_load_dwordx2 v[128:129], v[94:95], off offset:32
	global_load_dwordx4 v[130:133], v[186:187], off offset:128
	global_load_dwordx4 v[134:137], v[88:89], off offset:128
	global_load_dwordx2 v[100:101], v[92:93], off offset:64
	global_load_dwordx2 v[138:139], v[94:95], off offset:64
	global_load_dwordx4 v[140:143], v[186:187], off offset:192
	global_load_dwordx4 v[206:209], v[88:89], off offset:192
	global_load_dwordx2 v[110:111], v[92:93], off offset:96
	global_load_dwordx2 v[210:211], v[94:95], off offset:96
	s_waitcnt vmcnt(0)
	s_and_saveexec_b64 s[0:1], vcc
	s_cbranch_execz .LBB0_874
	v_pk_add_f32 v[74:75], v[98:99], v[68:69]
	v_pk_add_f32 v[72:73], v[62:63], v[70:71]
	v_pk_fma_f32 v[74:75], v[74:75], s[18:19], v[64:65] op_sel_hi:[1,0,1]
	v_pk_fma_f32 v[72:73], v[72:73], s[18:19], v[66:67] op_sel_hi:[1,0,1]
	v_lshlrev_b32_e32 v76, 16, v122
	v_and_b32_e32 v77, 0xffff0000, v122
	v_pk_mul_f32 v[74:75], v[74:75], v[76:77]
	s_nop 0
	v_cvt_pk_bf16_f32 v60, v74, v75
	v_lshlrev_b32_e32 v74, 16, v123
	v_and_b32_e32 v75, 0xffff0000, v123
	v_pk_mul_f32 v[72:73], v[72:73], v[74:75]
	s_nop 0
	v_cvt_pk_bf16_f32 v61, v72, v73
; DEVI unsigned pk2(float lo, float hi) { f32x2 v = {lo, hi}; bf16x2_t b = __builtin_convertvector(v, bf16x2_t); return __builtin_bit_cast(unsigned, b); }
; DEVI float bflo(unsigned u) { return __uint_as_float(u << 16); }
; DEVI float bfhi(unsigned u) { return __uint_as_float(u & 0xffff0000u); }
;     template <int MT> DEVI void operator()(f32x4 (&acc)[MT][4], int row0, int col0, int fr, int fq) const {
;     ...
;                 const f32x4 ys = acc[m][n] + qt[n];
;                 {
;                     const uint2 s = *(const uint2*)(p1 + 16 * n);
;                     const f32x4 v = (yc - ys) * scale + bb;
;                     o1[n].x = pk2(v[0] * bflo(s.x), v[1] * bfhi(s.x)); o1[n].y = pk2(v[2] * bflo(s.y), v[3] * bfhi(s.y));
;                 }
;                 o2[n].x = 0u; o2[n].y = 0u;
;                 if (k >= 1) {
;                     const uint2 s = *(const uint2*)(p2 + 16 * n);
;                     const f32x4 v = (yc + ys) * scale + bb;
;                     o2[n].x = pk2(v[0] * bflo(s.x), v[1] * bfhi(s.x)); o2[n].y = pk2(v[2] * bflo(s.y), v[3] * bfhi(s.y));
;                 }
;             }
;             const int wo = 16 * (fq & 1) + 8 * (fq >> 1) - 4 * fq;
; #pragma unroll
;             for (int n = 0; n < 4; n += 2) {
;                 const uint4 a1 = widen16(o1[n], o1[n + 1]), a2 = widen16(o2[n], o2[n + 1]);
;                 *(uint4*)(p1 + wo + 16 * n) = a1;
;                 if (k >= 1) *(uint4*)(p2 + wo + 16 * n) = a2;
;             }
.LBB0_874:
	s_or_b64 exec, exec, s[0:1]
	v_pk_add_f32 v[106:107], v[58:59], v[152:153]
	v_pk_add_f32 v[108:109], v[56:57], v[154:155]
	v_mov_b32_e32 v113, 0
	s_and_saveexec_b64 s[0:1], vcc
	s_cbranch_execz .LBB0_876
	v_pk_add_f32 v[58:59], v[106:107], v[82:83]
	v_pk_add_f32 v[72:73], v[108:109], v[80:81]
	v_pk_fma_f32 v[58:59], v[58:59], s[18:19], v[126:127] op_sel_hi:[1,0,1]
	v_pk_fma_f32 v[72:73], v[72:73], s[18:19], v[124:125] op_sel_hi:[1,0,1]
	v_lshlrev_b32_e32 v74, 16, v128
	v_and_b32_e32 v75, 0xffff0000, v128
	v_lshlrev_b32_e32 v56, 16, v129
	v_and_b32_e32 v57, 0xffff0000, v129
	v_pk_mul_f32 v[72:73], v[72:73], v[74:75]
	v_pk_mul_f32 v[56:57], v[58:59], v[56:57]
	v_cvt_pk_bf16_f32 v113, v72, v73
	v_cvt_pk_bf16_f32 v112, v56, v57
.LBB0_876:
	s_or_b64 exec, exec, s[0:1]
	v_pk_add_f32 v[54:55], v[54:55], v[158:159]
	v_pk_add_f32 v[102:103], v[52:53], v[160:161]
	v_mov_b32_e32 v114, 0
	v_mov_b32_e32 v53, 0
	v_mov_b32_e32 v52, 0
	s_and_saveexec_b64 s[0:1], vcc
	s_cbranch_execz .LBB0_878
	v_pk_add_f32 v[86:87], v[102:103], v[134:135]
	v_pk_add_f32 v[84:85], v[54:55], v[136:137]
	v_pk_fma_f32 v[86:87], v[86:87], s[18:19], v[130:131] op_sel_hi:[1,0,1]
	v_pk_fma_f32 v[84:85], v[84:85], s[18:19], v[132:133] op_sel_hi:[1,0,1]
	v_lshlrev_b32_e32 v90, 16, v138
	v_and_b32_e32 v91, 0xffff0000, v138
	v_pk_mul_f32 v[86:87], v[86:87], v[90:91]
	s_nop 0
	v_cvt_pk_bf16_f32 v52, v86, v87
	v_lshlrev_b32_e32 v86, 16, v139
	v_and_b32_e32 v87, 0xffff0000, v139
	v_pk_mul_f32 v[84:85], v[84:85], v[86:87]
	s_nop 0
	v_cvt_pk_bf16_f32 v53, v84, v85
.LBB0_878:
	s_or_b64 exec, exec, s[0:1]
	s_nop 0
	s_nop 0
	v_pk_add_f32 v[50:51], v[50:51], v[162:163]
	v_pk_add_f32 v[48:49], v[48:49], v[164:165]
	v_mov_b32_e32 v115, 0
	s_and_saveexec_b64 s[0:1], vcc
	s_cbranch_execz .LBB0_880
	v_pk_add_f32 v[114:115], v[50:51], v[208:209]
	v_pk_add_f32 v[118:119], v[48:49], v[206:207]
	v_pk_fma_f32 v[120:121], v[114:115], s[18:19], v[142:143] op_sel_hi:[1,0,1]
	v_pk_fma_f32 v[114:115], v[118:119], s[18:19], v[140:141] op_sel_hi:[1,0,1]
	v_lshlrev_b32_e32 v118, 16, v210
	v_and_b32_e32 v119, 0xffff0000, v210
	v_lshlrev_b32_e32 v116, 16, v211
	v_and_b32_e32 v117, 0xffff0000, v211
	v_pk_mul_f32 v[114:115], v[114:115], v[118:119]
	v_pk_mul_f32 v[116:117], v[120:121], v[116:117]
	v_cvt_pk_bf16_f32 v115, v114, v115
	v_cvt_pk_bf16_f32 v114, v116, v117
.LBB0_880:
	s_or_b64 exec, exec, s[0:1]
	v_sub_f32_e32 v81, v81, v109
	v_sub_f32_e32 v80, v80, v108
	v_sub_f32_e32 v83, v83, v107
	v_sub_f32_e32 v82, v82, v106
	v_pk_fma_f32 v[82:83], v[82:83], s[18:19], v[126:127] op_sel_hi:[1,0,1]
	v_pk_fma_f32 v[76:77], v[80:81], s[18:19], v[124:125] op_sel_hi:[1,0,1]
	v_lshlrev_b32_e32 v78, 16, v104
	v_and_b32_e32 v79, 0xffff0000, v104
	v_pk_mul_f32 v[76:77], v[76:77], v[78:79]
	v_sub_f32_e32 v69, v69, v99
	v_sub_f32_e32 v68, v68, v98
	v_sub_f32_e32 v63, v71, v63
	v_sub_f32_e32 v62, v70, v62
	v_cvt_pk_bf16_f32 v78, v76, v77
	v_lshlrev_b32_e32 v76, 16, v105
	v_and_b32_e32 v77, 0xffff0000, v105
	v_pk_fma_f32 v[62:63], v[62:63], s[18:19], v[66:67] op_sel_hi:[1,0,1]
	v_pk_fma_f32 v[64:65], v[68:69], s[18:19], v[64:65] op_sel_hi:[1,0,1]
	v_lshlrev_b32_e32 v66, 16, v96
	v_and_b32_e32 v67, 0xffff0000, v96
	v_pk_mul_f32 v[76:77], v[82:83], v[76:77]
	v_pk_mul_f32 v[64:65], v[64:65], v[66:67]
	v_cvt_pk_bf16_f32 v79, v76, v77
	v_cvt_pk_bf16_f32 v76, v64, v65
	v_lshlrev_b32_e32 v64, 16, v97
	v_and_b32_e32 v65, 0xffff0000, v97
	v_pk_mul_f32 v[62:63], v[62:63], v[64:65]
	v_lshl_add_u64 v[66:67], v[92:93], 0, v[156:157]
	v_cvt_pk_bf16_f32 v77, v62, v63
	v_lshl_add_u64 v[64:65], v[94:95], 0, v[156:157]
	v_permlane16_swap_b32_e32 v76, v78
	v_permlane16_swap_b32_e32 v77, v79
	v_permlane16_swap_b32_e32 v60, v113
	v_permlane16_swap_b32_e32 v61, v112
	global_store_dwordx4 v[66:67], v[76:79], off
	s_and_saveexec_b64 s[0:1], vcc
	s_cbranch_execz .LBB0_882
	v_mov_b32_e32 v62, v113
	v_mov_b32_e32 v63, v112
	global_store_dwordx4 v[64:65], v[60:63], off
.LBB0_882:
	s_or_b64 exec, exec, s[0:1]
	v_sub_f32_e32 v49, v207, v49
	v_sub_f32_e32 v48, v206, v48
	v_sub_f32_e32 v51, v209, v51
	v_sub_f32_e32 v50, v208, v50
	v_pk_fma_f32 v[60:61], v[50:51], s[18:19], v[142:143] op_sel_hi:[1,0,1]
	v_pk_fma_f32 v[48:49], v[48:49], s[18:19], v[140:141] op_sel_hi:[1,0,1]
	v_lshlrev_b32_e32 v50, 16, v110
	v_and_b32_e32 v51, 0xffff0000, v110
	v_pk_mul_f32 v[48:49], v[48:49], v[50:51]
	v_sub_f32_e32 v55, v137, v55
	v_cvt_pk_bf16_f32 v50, v48, v49
	v_lshlrev_b32_e32 v48, 16, v111
	v_and_b32_e32 v49, 0xffff0000, v111
	v_pk_mul_f32 v[48:49], v[60:61], v[48:49]
	v_sub_f32_e32 v54, v136, v54
	v_cvt_pk_bf16_f32 v51, v48, v49
	v_sub_f32_e32 v49, v135, v103
	v_sub_f32_e32 v48, v134, v102
	v_pk_fma_f32 v[48:49], v[48:49], s[18:19], v[130:131] op_sel_hi:[1,0,1]
	v_lshlrev_b32_e32 v56, 16, v100
	v_and_b32_e32 v57, 0xffff0000, v100
	v_pk_fma_f32 v[54:55], v[54:55], s[18:19], v[132:133] op_sel_hi:[1,0,1]
	v_pk_mul_f32 v[48:49], v[48:49], v[56:57]
	v_lshlrev_b32_e32 v56, 16, v101
	v_and_b32_e32 v57, 0xffff0000, v101
	v_pk_mul_f32 v[54:55], v[54:55], v[56:57]
	v_cvt_pk_bf16_f32 v48, v48, v49
	v_cvt_pk_bf16_f32 v49, v54, v55
	s_nop 0
	v_permlane16_swap_b32_e32 v48, v50
	v_permlane16_swap_b32_e32 v49, v51
	v_permlane16_swap_b32_e32 v52, v115
	v_permlane16_swap_b32_e32 v53, v114
	global_store_dwordx4 v[66:67], v[48:51], off offset:64
	s_and_saveexec_b64 s[0:1], vcc
	s_cbranch_execz .LBB0_884
	v_mov_b32_e32 v54, v115
	v_mov_b32_e32 v55, v114
	global_store_dwordx4 v[64:65], v[52:55], off offset:64
; DEVI unsigned pk2(float lo, float hi) { f32x2 v = {lo, hi}; bf16x2_t b = __builtin_convertvector(v, bf16x2_t); return __builtin_bit_cast(unsigned, b); }
; DEVI float bflo(unsigned u) { return __uint_as_float(u << 16); }
; DEVI float bfhi(unsigned u) { return __uint_as_float(u & 0xffff0000u); }
;     template <int MT> DEVI void operator()(f32x4 (&acc)[MT][4], int row0, int col0, int fr, int fq) const {
;     ...
;             const int kp = row0 + 16 * m + fr, k = 2 * kp + par;
;             const float* trow = T + ((size_t)((b * 2 + par) * 1024 + kp)) * 1024 + col0 + 4 * fq;
;             bf16_t* p1 = sgf + (size_t)(b * TPB + CTX + k) * 1024 + col0 + 4 * fq;
;             bf16_t* p2 = sgf + (size_t)(b * TPB + CTX + 4096 - k) * 1024 + col0 + 4 * fq;
;             uint2 o1[4], o2[4];
; #pragma unroll
;             for (int n = 0; n < 4; ++n) {
;                 const f32x4 bb = *(const f32x4*)(bfv + col0 + 16 * n + 4 * fq);
;                 const f32x4 yc = *(const f32x4*)(trow + 16 * n);
;                 const f32x4 ys = acc[m][n] + qt[n];
;                 {
;                     const uint2 s = *(const uint2*)(p1 + 16 * n);
;                     const f32x4 v = (yc - ys) * scale + bb;
;                     o1[n].x = pk2(v[0] * bflo(s.x), v[1] * bfhi(s.x)); o1[n].y = pk2(v[2] * bflo(s.y), v[3] * bfhi(s.y));
;                 }
;                 o2[n].x = 0u; o2[n].y = 0u;
;                 if (k >= 1) {
;                     const uint2 s = *(const uint2*)(p2 + 16 * n);
;                     const f32x4 v = (yc + ys) * scale + bb;
;                     o2[n].x = pk2(v[0] * bflo(s.x), v[1] * bfhi(s.x)); o2[n].y = pk2(v[2] * bflo(s.y), v[3] * bfhi(s.y));
;                 }
.LBB0_884:
	s_or_b64 exec, exec, s[0:1]
	v_or_b32_e32 v48, 0x50, v173
	v_lshl_or_b32 v58, v48, 1, s71
	v_add_u32_e32 v48, s29, v48
	v_ashrrev_i32_e32 v49, 31, v48
	v_lshlrev_b64 v[48:49], 12, v[48:49]
	v_lshl_add_u64 v[48:49], s[40:41], 0, v[48:49]
	v_lshl_add_u64 v[48:49], v[48:49], 0, v[184:185]
	v_mov_b32_e32 v151, v185
	v_lshl_add_u64 v[72:73], v[48:49], 0, v[150:151]
	v_add_u32_e32 v48, s28, v58
	v_ashrrev_i32_e32 v49, 31, v48
	v_lshlrev_b64 v[48:49], 11, v[48:49]
	v_lshl_add_u64 v[48:49], s[54:55], 0, v[48:49]
	v_mov_b32_e32 v189, v185
	v_lshl_add_u64 v[48:49], v[48:49], 0, v[188:189]
	v_mov_b32_e32 v149, v185
	v_lshl_add_u64 v[76:77], v[48:49], 0, v[148:149]
	global_load_dwordx4 v[48:51], v[186:187], off
	global_load_dwordx4 v[52:55], v[72:73], off
	global_load_dwordx2 v[80:81], v[76:77], off
	v_sub_u32_e32 v56, s30, v58
	v_ashrrev_i32_e32 v57, 31, v56
	v_lshlrev_b64 v[56:57], 11, v[56:57]
	v_lshl_add_u64 v[56:57], s[54:55], 0, v[56:57]
	v_lshl_add_u64 v[56:57], v[56:57], 0, v[188:189]
	v_lshl_add_u64 v[78:79], v[56:57], 0, v[148:149]
	v_mov_b32_e32 v96, 0
	v_cmp_lt_i32_e32 vcc, 0, v58
	v_pk_add_f32 v[46:47], v[46:47], v[144:145]
	v_pk_add_f32 v[82:83], v[44:45], v[146:147]
	v_mov_b32_e32 v45, 0
	v_mov_b32_e32 v44, 0
	global_load_dwordx2 v[106:107], v[78:79], off
	global_load_dwordx4 v[108:111], v[186:187], off offset:64
	global_load_dwordx4 v[64:67], v[72:73], off offset:64
	global_load_dwordx2 v[88:89], v[76:77], off offset:32
	global_load_dwordx2 v[112:113], v[78:79], off offset:32
	global_load_dwordx4 v[114:117], v[186:187], off offset:128
	global_load_dwordx4 v[118:121], v[72:73], off offset:128
	global_load_dwordx2 v[84:85], v[76:77], off offset:64
	global_load_dwordx2 v[122:123], v[78:79], off offset:64
	global_load_dwordx4 v[124:127], v[186:187], off offset:192
	global_load_dwordx4 v[128:131], v[72:73], off offset:192
	global_load_dwordx2 v[94:95], v[76:77], off offset:96
	global_load_dwordx2 v[132:133], v[78:79], off offset:96
	s_waitcnt vmcnt(0)
	s_and_saveexec_b64 s[0:1], vcc
	s_cbranch_execz .LBB0_886
	v_pk_add_f32 v[58:59], v[82:83], v[52:53]
	v_pk_add_f32 v[56:57], v[46:47], v[54:55]
	v_pk_fma_f32 v[58:59], v[58:59], s[18:19], v[48:49] op_sel_hi:[1,0,1]
	v_pk_fma_f32 v[56:57], v[56:57], s[18:19], v[50:51] op_sel_hi:[1,0,1]
	v_lshlrev_b32_e32 v60, 16, v106
	v_and_b32_e32 v61, 0xffff0000, v106
	v_pk_mul_f32 v[58:59], v[58:59], v[60:61]
	s_nop 0
	v_cvt_pk_bf16_f32 v44, v58, v59
	v_lshlrev_b32_e32 v58, 16, v107
	v_and_b32_e32 v59, 0xffff0000, v107
	v_pk_mul_f32 v[56:57], v[56:57], v[58:59]
	s_nop 0
	v_cvt_pk_bf16_f32 v45, v56, v57
.LBB0_886:
	s_or_b64 exec, exec, s[0:1]
	v_pk_add_f32 v[90:91], v[42:43], v[152:153]
	v_pk_add_f32 v[92:93], v[40:41], v[154:155]
	v_mov_b32_e32 v97, 0
	s_and_saveexec_b64 s[0:1], vcc
	s_cbranch_execz .LBB0_888
	v_pk_add_f32 v[42:43], v[90:91], v[66:67]
	v_pk_add_f32 v[56:57], v[92:93], v[64:65]
	v_pk_fma_f32 v[42:43], v[42:43], s[18:19], v[110:111] op_sel_hi:[1,0,1]
	v_pk_fma_f32 v[56:57], v[56:57], s[18:19], v[108:109] op_sel_hi:[1,0,1]
	v_lshlrev_b32_e32 v58, 16, v112
	v_and_b32_e32 v59, 0xffff0000, v112
	v_lshlrev_b32_e32 v40, 16, v113
	v_and_b32_e32 v41, 0xffff0000, v113
	v_pk_mul_f32 v[56:57], v[56:57], v[58:59]
	v_pk_mul_f32 v[40:41], v[42:43], v[40:41]
	v_cvt_pk_bf16_f32 v97, v56, v57
	v_cvt_pk_bf16_f32 v96, v40, v41
.LBB0_888:
	s_or_b64 exec, exec, s[0:1]
	v_pk_add_f32 v[38:39], v[38:39], v[158:159]
	v_pk_add_f32 v[86:87], v[36:37], v[160:161]
	v_mov_b32_e32 v98, 0
	v_mov_b32_e32 v37, 0
	v_mov_b32_e32 v36, 0
	s_and_saveexec_b64 s[0:1], vcc
	s_cbranch_execz .LBB0_890
	v_pk_add_f32 v[70:71], v[86:87], v[118:119]
	v_pk_add_f32 v[68:69], v[38:39], v[120:121]
	v_pk_fma_f32 v[70:71], v[70:71], s[18:19], v[114:115] op_sel_hi:[1,0,1]
	v_pk_fma_f32 v[68:69], v[68:69], s[18:19], v[116:117] op_sel_hi:[1,0,1]
	v_lshlrev_b32_e32 v74, 16, v122
	v_and_b32_e32 v75, 0xffff0000, v122
	v_pk_mul_f32 v[70:71], v[70:71], v[74:75]
	s_nop 0
	v_cvt_pk_bf16_f32 v36, v70, v71
	v_lshlrev_b32_e32 v70, 16, v123
	v_and_b32_e32 v71, 0xffff0000, v123
	v_pk_mul_f32 v[68:69], v[68:69], v[70:71]
	s_nop 0
	v_cvt_pk_bf16_f32 v37, v68, v69
.LBB0_890:
	s_or_b64 exec, exec, s[0:1]
	s_nop 0
	s_nop 0
	v_pk_add_f32 v[34:35], v[34:35], v[162:163]
	v_pk_add_f32 v[32:33], v[32:33], v[164:165]
	v_mov_b32_e32 v99, 0
	s_and_saveexec_b64 s[0:1], vcc
	s_cbranch_execz .LBB0_892
	v_pk_add_f32 v[98:99], v[34:35], v[130:131]
	v_pk_add_f32 v[102:103], v[32:33], v[128:129]
	v_pk_fma_f32 v[104:105], v[98:99], s[18:19], v[126:127] op_sel_hi:[1,0,1]
	v_pk_fma_f32 v[98:99], v[102:103], s[18:19], v[124:125] op_sel_hi:[1,0,1]
	v_lshlrev_b32_e32 v102, 16, v132
	v_and_b32_e32 v103, 0xffff0000, v132
	v_lshlrev_b32_e32 v100, 16, v133
	v_and_b32_e32 v101, 0xffff0000, v133
	v_pk_mul_f32 v[98:99], v[98:99], v[102:103]
	v_pk_mul_f32 v[100:101], v[104:105], v[100:101]
	v_cvt_pk_bf16_f32 v99, v98, v99
	v_cvt_pk_bf16_f32 v98, v100, v101
; DEVI unsigned pk2(float lo, float hi) { f32x2 v = {lo, hi}; bf16x2_t b = __builtin_convertvector(v, bf16x2_t); return __builtin_bit_cast(unsigned, b); }
; DEVI float bflo(unsigned u) { return __uint_as_float(u << 16); }
; DEVI float bfhi(unsigned u) { return __uint_as_float(u & 0xffff0000u); }
;     template <int MT> DEVI void operator()(f32x4 (&acc)[MT][4], int row0, int col0, int fr, int fq) const {
;     ...
;             const int kp = row0 + 16 * m + fr, k = 2 * kp + par;
;             const float* trow = T + ((size_t)((b * 2 + par) * 1024 + kp)) * 1024 + col0 + 4 * fq;
;             bf16_t* p1 = sgf + (size_t)(b * TPB + CTX + k) * 1024 + col0 + 4 * fq;
;             bf16_t* p2 = sgf + (size_t)(b * TPB + CTX + 4096 - k) * 1024 + col0 + 4 * fq;
;             uint2 o1[4], o2[4];
; #pragma unroll
;             for (int n = 0; n < 4; ++n) {
;                 const f32x4 bb = *(const f32x4*)(bfv + col0 + 16 * n + 4 * fq);
;                 const f32x4 yc = *(const f32x4*)(trow + 16 * n);
;                 const f32x4 ys = acc[m][n] + qt[n];
;                 {
;                     const uint2 s = *(const uint2*)(p1 + 16 * n);
;                     const f32x4 v = (yc - ys) * scale + bb;
;                     o1[n].x = pk2(v[0] * bflo(s.x), v[1] * bfhi(s.x)); o1[n].y = pk2(v[2] * bflo(s.y), v[3] * bfhi(s.y));
;                 }
;                 o2[n].x = 0u; o2[n].y = 0u;
;                 if (k >= 1) {
;                     const uint2 s = *(const uint2*)(p2 + 16 * n);
;                     const f32x4 v = (yc + ys) * scale + bb;
;                     o2[n].x = pk2(v[0] * bflo(s.x), v[1] * bfhi(s.x)); o2[n].y = pk2(v[2] * bflo(s.y), v[3] * bfhi(s.y));
;                 }
;             }
;             const int wo = 16 * (fq & 1) + 8 * (fq >> 1) - 4 * fq;
; #pragma unroll
;             for (int n = 0; n < 4; n += 2) {
;                 const uint4 a1 = widen16(o1[n], o1[n + 1]), a2 = widen16(o2[n], o2[n + 1]);
;                 *(uint4*)(p1 + wo + 16 * n) = a1;
;                 if (k >= 1) *(uint4*)(p2 + wo + 16 * n) = a2;
;             }
.LBB0_892:
	s_or_b64 exec, exec, s[0:1]
	v_sub_f32_e32 v65, v65, v93
	v_sub_f32_e32 v64, v64, v92
	v_sub_f32_e32 v67, v67, v91
	v_sub_f32_e32 v66, v66, v90
	v_pk_fma_f32 v[66:67], v[66:67], s[18:19], v[110:111] op_sel_hi:[1,0,1]
	v_pk_fma_f32 v[60:61], v[64:65], s[18:19], v[108:109] op_sel_hi:[1,0,1]
	v_lshlrev_b32_e32 v62, 16, v88
	v_and_b32_e32 v63, 0xffff0000, v88
	v_pk_mul_f32 v[60:61], v[60:61], v[62:63]
	v_sub_f32_e32 v53, v53, v83
	v_sub_f32_e32 v52, v52, v82
	v_sub_f32_e32 v47, v55, v47
	v_sub_f32_e32 v46, v54, v46
	v_cvt_pk_bf16_f32 v62, v60, v61
	v_lshlrev_b32_e32 v60, 16, v89
	v_and_b32_e32 v61, 0xffff0000, v89
	v_pk_fma_f32 v[46:47], v[46:47], s[18:19], v[50:51] op_sel_hi:[1,0,1]
	v_pk_fma_f32 v[48:49], v[52:53], s[18:19], v[48:49] op_sel_hi:[1,0,1]
	v_lshlrev_b32_e32 v50, 16, v80
	v_and_b32_e32 v51, 0xffff0000, v80
	v_pk_mul_f32 v[60:61], v[66:67], v[60:61]
	v_pk_mul_f32 v[48:49], v[48:49], v[50:51]
	v_cvt_pk_bf16_f32 v63, v60, v61
	v_cvt_pk_bf16_f32 v60, v48, v49
	v_lshlrev_b32_e32 v48, 16, v81
	v_and_b32_e32 v49, 0xffff0000, v81
	v_pk_mul_f32 v[46:47], v[46:47], v[48:49]
	v_lshl_add_u64 v[50:51], v[76:77], 0, v[156:157]
	v_cvt_pk_bf16_f32 v61, v46, v47
	v_lshl_add_u64 v[48:49], v[78:79], 0, v[156:157]
	v_permlane16_swap_b32_e32 v60, v62
	v_permlane16_swap_b32_e32 v61, v63
	v_permlane16_swap_b32_e32 v44, v97
	v_permlane16_swap_b32_e32 v45, v96
	global_store_dwordx4 v[50:51], v[60:63], off
	s_and_saveexec_b64 s[0:1], vcc
	s_cbranch_execz .LBB0_894
	v_mov_b32_e32 v46, v97
	v_mov_b32_e32 v47, v96
	global_store_dwordx4 v[48:49], v[44:47], off
.LBB0_894:
	s_or_b64 exec, exec, s[0:1]
	v_sub_f32_e32 v33, v129, v33
	v_sub_f32_e32 v32, v128, v32
	v_sub_f32_e32 v35, v131, v35
	v_sub_f32_e32 v34, v130, v34
	v_pk_fma_f32 v[44:45], v[34:35], s[18:19], v[126:127] op_sel_hi:[1,0,1]
	v_pk_fma_f32 v[32:33], v[32:33], s[18:19], v[124:125] op_sel_hi:[1,0,1]
	v_lshlrev_b32_e32 v34, 16, v94
	v_and_b32_e32 v35, 0xffff0000, v94
	v_pk_mul_f32 v[32:33], v[32:33], v[34:35]
	v_sub_f32_e32 v39, v121, v39
	v_cvt_pk_bf16_f32 v34, v32, v33
	v_lshlrev_b32_e32 v32, 16, v95
	v_and_b32_e32 v33, 0xffff0000, v95
	v_pk_mul_f32 v[32:33], v[44:45], v[32:33]
	v_sub_f32_e32 v38, v120, v38
	v_cvt_pk_bf16_f32 v35, v32, v33
	v_sub_f32_e32 v33, v119, v87
	v_sub_f32_e32 v32, v118, v86
	v_pk_fma_f32 v[32:33], v[32:33], s[18:19], v[114:115] op_sel_hi:[1,0,1]
	v_lshlrev_b32_e32 v40, 16, v84
	v_and_b32_e32 v41, 0xffff0000, v84
	v_pk_fma_f32 v[38:39], v[38:39], s[18:19], v[116:117] op_sel_hi:[1,0,1]
	v_pk_mul_f32 v[32:33], v[32:33], v[40:41]
	v_lshlrev_b32_e32 v40, 16, v85
	v_and_b32_e32 v41, 0xffff0000, v85
	v_pk_mul_f32 v[38:39], v[38:39], v[40:41]
	v_cvt_pk_bf16_f32 v32, v32, v33
	v_cvt_pk_bf16_f32 v33, v38, v39
	s_nop 0
	v_permlane16_swap_b32_e32 v32, v34
	v_permlane16_swap_b32_e32 v33, v35
	v_permlane16_swap_b32_e32 v36, v99
	v_permlane16_swap_b32_e32 v37, v98
	global_store_dwordx4 v[50:51], v[32:35], off offset:64
	s_and_saveexec_b64 s[0:1], vcc
	s_cbranch_execz .LBB0_896
	v_mov_b32_e32 v38, v99
	v_mov_b32_e32 v39, v98
	global_store_dwordx4 v[48:49], v[36:39], off offset:64
.LBB0_896:
	s_or_b64 exec, exec, s[0:1]
	v_or_b32_e32 v32, 0x60, v173
	v_lshl_or_b32 v42, v32, 1, s71
	v_add_u32_e32 v32, s29, v32
	v_ashrrev_i32_e32 v33, 31, v32
	v_lshlrev_b64 v[32:33], 12, v[32:33]
	v_lshl_add_u64 v[32:33], s[40:41], 0, v[32:33]
	v_lshl_add_u64 v[32:33], v[32:33], 0, v[184:185]
	v_mov_b32_e32 v151, v185
	v_lshl_add_u64 v[56:57], v[32:33], 0, v[150:151]
	v_add_u32_e32 v32, s28, v42
	v_ashrrev_i32_e32 v33, 31, v32
	v_lshlrev_b64 v[32:33], 11, v[32:33]
	v_lshl_add_u64 v[32:33], s[54:55], 0, v[32:33]
	v_mov_b32_e32 v189, v185
	v_lshl_add_u64 v[32:33], v[32:33], 0, v[188:189]
	v_mov_b32_e32 v149, v185
	v_lshl_add_u64 v[60:61], v[32:33], 0, v[148:149]
	global_load_dwordx4 v[32:35], v[186:187], off
	global_load_dwordx4 v[36:39], v[56:57], off
	global_load_dwordx2 v[64:65], v[60:61], off
	v_sub_u32_e32 v40, s30, v42
	v_ashrrev_i32_e32 v41, 31, v40
	v_lshlrev_b64 v[40:41], 11, v[40:41]
	v_lshl_add_u64 v[40:41], s[54:55], 0, v[40:41]
	v_lshl_add_u64 v[40:41], v[40:41], 0, v[188:189]
	v_lshl_add_u64 v[62:63], v[40:41], 0, v[148:149]
	v_mov_b32_e32 v80, 0
	v_cmp_lt_i32_e32 vcc, 0, v42
	v_pk_add_f32 v[30:31], v[30:31], v[144:145]
	v_pk_add_f32 v[66:67], v[28:29], v[146:147]
	v_mov_b32_e32 v29, 0
	v_mov_b32_e32 v28, 0
	global_load_dwordx2 v[90:91], v[62:63], off
	global_load_dwordx4 v[92:95], v[186:187], off offset:64
	global_load_dwordx4 v[48:51], v[56:57], off offset:64
	global_load_dwordx2 v[72:73], v[60:61], off offset:32
	global_load_dwordx2 v[96:97], v[62:63], off offset:32
	global_load_dwordx4 v[98:101], v[186:187], off offset:128
	global_load_dwordx4 v[102:105], v[56:57], off offset:128
	global_load_dwordx2 v[68:69], v[60:61], off offset:64
	global_load_dwordx2 v[106:107], v[62:63], off offset:64
	global_load_dwordx4 v[108:111], v[186:187], off offset:192
	global_load_dwordx4 v[112:115], v[56:57], off offset:192
	global_load_dwordx2 v[78:79], v[60:61], off offset:96
	global_load_dwordx2 v[116:117], v[62:63], off offset:96
	s_waitcnt vmcnt(0)
	s_and_saveexec_b64 s[0:1], vcc
	s_cbranch_execz .LBB0_898
	v_pk_add_f32 v[42:43], v[66:67], v[36:37]
	v_pk_add_f32 v[40:41], v[30:31], v[38:39]
	v_pk_fma_f32 v[42:43], v[42:43], s[18:19], v[32:33] op_sel_hi:[1,0,1]
	v_pk_fma_f32 v[40:41], v[40:41], s[18:19], v[34:35] op_sel_hi:[1,0,1]
	v_lshlrev_b32_e32 v44, 16, v90
	v_and_b32_e32 v45, 0xffff0000, v90
	v_pk_mul_f32 v[42:43], v[42:43], v[44:45]
	s_nop 0
	v_cvt_pk_bf16_f32 v28, v42, v43
	v_lshlrev_b32_e32 v42, 16, v91
	v_and_b32_e32 v43, 0xffff0000, v91
	v_pk_mul_f32 v[40:41], v[40:41], v[42:43]
	s_nop 0
	v_cvt_pk_bf16_f32 v29, v40, v41
; DEVI unsigned pk2(float lo, float hi) { f32x2 v = {lo, hi}; bf16x2_t b = __builtin_convertvector(v, bf16x2_t); return __builtin_bit_cast(unsigned, b); }
; DEVI float bflo(unsigned u) { return __uint_as_float(u << 16); }
; DEVI float bfhi(unsigned u) { return __uint_as_float(u & 0xffff0000u); }
;     template <int MT> DEVI void operator()(f32x4 (&acc)[MT][4], int row0, int col0, int fr, int fq) const {
;     ...
;                 const f32x4 ys = acc[m][n] + qt[n];
;                 {
;                     const uint2 s = *(const uint2*)(p1 + 16 * n);
;                     const f32x4 v = (yc - ys) * scale + bb;
;                     o1[n].x = pk2(v[0] * bflo(s.x), v[1] * bfhi(s.x)); o1[n].y = pk2(v[2] * bflo(s.y), v[3] * bfhi(s.y));
;                 }
;                 o2[n].x = 0u; o2[n].y = 0u;
;                 if (k >= 1) {
;                     const uint2 s = *(const uint2*)(p2 + 16 * n);
;                     const f32x4 v = (yc + ys) * scale + bb;
;                     o2[n].x = pk2(v[0] * bflo(s.x), v[1] * bfhi(s.x)); o2[n].y = pk2(v[2] * bflo(s.y), v[3] * bfhi(s.y));
;                 }
;             }
;             const int wo = 16 * (fq & 1) + 8 * (fq >> 1) - 4 * fq;
; #pragma unroll
;             for (int n = 0; n < 4; n += 2) {
;                 const uint4 a1 = widen16(o1[n], o1[n + 1]), a2 = widen16(o2[n], o2[n + 1]);
;                 *(uint4*)(p1 + wo + 16 * n) = a1;
;                 if (k >= 1) *(uint4*)(p2 + wo + 16 * n) = a2;
;             }
.LBB0_898:
	s_or_b64 exec, exec, s[0:1]
	v_pk_add_f32 v[74:75], v[26:27], v[152:153]
	v_pk_add_f32 v[76:77], v[24:25], v[154:155]
	v_mov_b32_e32 v81, 0
	s_and_saveexec_b64 s[0:1], vcc
	s_cbranch_execz .LBB0_900
	v_pk_add_f32 v[26:27], v[74:75], v[50:51]
	v_pk_add_f32 v[40:41], v[76:77], v[48:49]
	v_pk_fma_f32 v[26:27], v[26:27], s[18:19], v[94:95] op_sel_hi:[1,0,1]
	v_pk_fma_f32 v[40:41], v[40:41], s[18:19], v[92:93] op_sel_hi:[1,0,1]
	v_lshlrev_b32_e32 v42, 16, v96
	v_and_b32_e32 v43, 0xffff0000, v96
	v_lshlrev_b32_e32 v24, 16, v97
	v_and_b32_e32 v25, 0xffff0000, v97
	v_pk_mul_f32 v[40:41], v[40:41], v[42:43]
	v_pk_mul_f32 v[24:25], v[26:27], v[24:25]
	v_cvt_pk_bf16_f32 v81, v40, v41
	v_cvt_pk_bf16_f32 v80, v24, v25
.LBB0_900:
	s_or_b64 exec, exec, s[0:1]
	v_pk_add_f32 v[22:23], v[22:23], v[158:159]
	v_pk_add_f32 v[70:71], v[20:21], v[160:161]
	v_mov_b32_e32 v82, 0
	v_mov_b32_e32 v21, 0
	v_mov_b32_e32 v20, 0
	s_and_saveexec_b64 s[0:1], vcc
	s_cbranch_execz .LBB0_902
	v_pk_add_f32 v[54:55], v[70:71], v[102:103]
	v_pk_add_f32 v[52:53], v[22:23], v[104:105]
	v_pk_fma_f32 v[54:55], v[54:55], s[18:19], v[98:99] op_sel_hi:[1,0,1]
	v_pk_fma_f32 v[52:53], v[52:53], s[18:19], v[100:101] op_sel_hi:[1,0,1]
	v_lshlrev_b32_e32 v58, 16, v106
	v_and_b32_e32 v59, 0xffff0000, v106
	v_pk_mul_f32 v[54:55], v[54:55], v[58:59]
	s_nop 0
	v_cvt_pk_bf16_f32 v20, v54, v55
	v_lshlrev_b32_e32 v54, 16, v107
	v_and_b32_e32 v55, 0xffff0000, v107
	v_pk_mul_f32 v[52:53], v[52:53], v[54:55]
	s_nop 0
	v_cvt_pk_bf16_f32 v21, v52, v53
.LBB0_902:
	s_or_b64 exec, exec, s[0:1]
	s_nop 0
	s_nop 0
	v_pk_add_f32 v[18:19], v[18:19], v[162:163]
	v_pk_add_f32 v[16:17], v[16:17], v[164:165]
	v_mov_b32_e32 v83, 0
	s_and_saveexec_b64 s[0:1], vcc
	s_cbranch_execz .LBB0_904
	v_pk_add_f32 v[82:83], v[18:19], v[114:115]
	v_pk_add_f32 v[86:87], v[16:17], v[112:113]
	v_pk_fma_f32 v[88:89], v[82:83], s[18:19], v[110:111] op_sel_hi:[1,0,1]
	v_pk_fma_f32 v[82:83], v[86:87], s[18:19], v[108:109] op_sel_hi:[1,0,1]
	v_lshlrev_b32_e32 v86, 16, v116
	v_and_b32_e32 v87, 0xffff0000, v116
	v_lshlrev_b32_e32 v84, 16, v117
	v_and_b32_e32 v85, 0xffff0000, v117
	v_pk_mul_f32 v[82:83], v[82:83], v[86:87]
	v_pk_mul_f32 v[84:85], v[88:89], v[84:85]
	v_cvt_pk_bf16_f32 v83, v82, v83
	v_cvt_pk_bf16_f32 v82, v84, v85
.LBB0_904:
	s_or_b64 exec, exec, s[0:1]
	v_sub_f32_e32 v49, v49, v77
	v_sub_f32_e32 v48, v48, v76
	v_sub_f32_e32 v51, v51, v75
	v_sub_f32_e32 v50, v50, v74
	v_pk_fma_f32 v[50:51], v[50:51], s[18:19], v[94:95] op_sel_hi:[1,0,1]
	v_pk_fma_f32 v[44:45], v[48:49], s[18:19], v[92:93] op_sel_hi:[1,0,1]
	v_lshlrev_b32_e32 v46, 16, v72
	v_and_b32_e32 v47, 0xffff0000, v72
	v_pk_mul_f32 v[44:45], v[44:45], v[46:47]
	v_sub_f32_e32 v37, v37, v67
	v_sub_f32_e32 v36, v36, v66
	v_sub_f32_e32 v31, v39, v31
	v_sub_f32_e32 v30, v38, v30
	v_cvt_pk_bf16_f32 v46, v44, v45
	v_lshlrev_b32_e32 v44, 16, v73
	v_and_b32_e32 v45, 0xffff0000, v73
	v_pk_fma_f32 v[30:31], v[30:31], s[18:19], v[34:35] op_sel_hi:[1,0,1]
	v_pk_fma_f32 v[32:33], v[36:37], s[18:19], v[32:33] op_sel_hi:[1,0,1]
	v_lshlrev_b32_e32 v34, 16, v64
	v_and_b32_e32 v35, 0xffff0000, v64
	v_pk_mul_f32 v[44:45], v[50:51], v[44:45]
	v_pk_mul_f32 v[32:33], v[32:33], v[34:35]
	v_cvt_pk_bf16_f32 v47, v44, v45
	v_cvt_pk_bf16_f32 v44, v32, v33
	v_lshlrev_b32_e32 v32, 16, v65
	v_and_b32_e32 v33, 0xffff0000, v65
	v_pk_mul_f32 v[30:31], v[30:31], v[32:33]
	v_lshl_add_u64 v[34:35], v[60:61], 0, v[156:157]
	v_cvt_pk_bf16_f32 v45, v30, v31
	v_lshl_add_u64 v[32:33], v[62:63], 0, v[156:157]
	v_permlane16_swap_b32_e32 v44, v46
	v_permlane16_swap_b32_e32 v45, v47
	v_permlane16_swap_b32_e32 v28, v81
	v_permlane16_swap_b32_e32 v29, v80
	global_store_dwordx4 v[34:35], v[44:47], off
	s_and_saveexec_b64 s[0:1], vcc
	s_cbranch_execz .LBB0_906
	v_mov_b32_e32 v30, v81
	v_mov_b32_e32 v31, v80
	global_store_dwordx4 v[32:33], v[28:31], off
.LBB0_906:
	s_or_b64 exec, exec, s[0:1]
	v_sub_f32_e32 v17, v113, v17
	v_sub_f32_e32 v16, v112, v16
	v_sub_f32_e32 v19, v115, v19
	v_sub_f32_e32 v18, v114, v18
	v_pk_fma_f32 v[28:29], v[18:19], s[18:19], v[110:111] op_sel_hi:[1,0,1]
	v_pk_fma_f32 v[16:17], v[16:17], s[18:19], v[108:109] op_sel_hi:[1,0,1]
	v_lshlrev_b32_e32 v18, 16, v78
	v_and_b32_e32 v19, 0xffff0000, v78
	v_pk_mul_f32 v[16:17], v[16:17], v[18:19]
	v_sub_f32_e32 v23, v105, v23
	v_cvt_pk_bf16_f32 v18, v16, v17
	v_lshlrev_b32_e32 v16, 16, v79
	v_and_b32_e32 v17, 0xffff0000, v79
	v_pk_mul_f32 v[16:17], v[28:29], v[16:17]
	v_sub_f32_e32 v22, v104, v22
	v_cvt_pk_bf16_f32 v19, v16, v17
	v_sub_f32_e32 v17, v103, v71
	v_sub_f32_e32 v16, v102, v70
	v_pk_fma_f32 v[16:17], v[16:17], s[18:19], v[98:99] op_sel_hi:[1,0,1]
	v_lshlrev_b32_e32 v24, 16, v68
	v_and_b32_e32 v25, 0xffff0000, v68
	v_pk_fma_f32 v[22:23], v[22:23], s[18:19], v[100:101] op_sel_hi:[1,0,1]
	v_pk_mul_f32 v[16:17], v[16:17], v[24:25]
	v_lshlrev_b32_e32 v24, 16, v69
	v_and_b32_e32 v25, 0xffff0000, v69
	v_pk_mul_f32 v[22:23], v[22:23], v[24:25]
	v_cvt_pk_bf16_f32 v16, v16, v17
	v_cvt_pk_bf16_f32 v17, v22, v23
	s_nop 0
	v_permlane16_swap_b32_e32 v16, v18
	v_permlane16_swap_b32_e32 v17, v19
	v_permlane16_swap_b32_e32 v20, v83
	v_permlane16_swap_b32_e32 v21, v82
	global_store_dwordx4 v[34:35], v[16:19], off offset:64
	s_and_saveexec_b64 s[0:1], vcc
	s_cbranch_execz .LBB0_908
	v_mov_b32_e32 v22, v83
	v_mov_b32_e32 v23, v82
	global_store_dwordx4 v[32:33], v[20:23], off offset:64
; DEVI unsigned pk2(float lo, float hi) { f32x2 v = {lo, hi}; bf16x2_t b = __builtin_convertvector(v, bf16x2_t); return __builtin_bit_cast(unsigned, b); }
; DEVI float bflo(unsigned u) { return __uint_as_float(u << 16); }
; DEVI float bfhi(unsigned u) { return __uint_as_float(u & 0xffff0000u); }
;     template <int MT> DEVI void operator()(f32x4 (&acc)[MT][4], int row0, int col0, int fr, int fq) const {
;     ...
;             const int kp = row0 + 16 * m + fr, k = 2 * kp + par;
;             const float* trow = T + ((size_t)((b * 2 + par) * 1024 + kp)) * 1024 + col0 + 4 * fq;
;             bf16_t* p1 = sgf + (size_t)(b * TPB + CTX + k) * 1024 + col0 + 4 * fq;
;             bf16_t* p2 = sgf + (size_t)(b * TPB + CTX + 4096 - k) * 1024 + col0 + 4 * fq;
;             uint2 o1[4], o2[4];
; #pragma unroll
;             for (int n = 0; n < 4; ++n) {
;                 const f32x4 bb = *(const f32x4*)(bfv + col0 + 16 * n + 4 * fq);
;                 const f32x4 yc = *(const f32x4*)(trow + 16 * n);
;                 const f32x4 ys = acc[m][n] + qt[n];
;                 {
;                     const uint2 s = *(const uint2*)(p1 + 16 * n);
;                     const f32x4 v = (yc - ys) * scale + bb;
;                     o1[n].x = pk2(v[0] * bflo(s.x), v[1] * bfhi(s.x)); o1[n].y = pk2(v[2] * bflo(s.y), v[3] * bfhi(s.y));
;                 }
;                 o2[n].x = 0u; o2[n].y = 0u;
;                 if (k >= 1) {
;                     const uint2 s = *(const uint2*)(p2 + 16 * n);
;                     const f32x4 v = (yc + ys) * scale + bb;
;                     o2[n].x = pk2(v[0] * bflo(s.x), v[1] * bfhi(s.x)); o2[n].y = pk2(v[2] * bflo(s.y), v[3] * bfhi(s.y));
;                 }
.LBB0_908:
	s_or_b64 exec, exec, s[0:1]
	v_or_b32_e32 v16, 0x70, v173
	v_lshl_or_b32 v26, v16, 1, s71
	v_add_u32_e32 v16, s29, v16
	v_ashrrev_i32_e32 v17, 31, v16
	v_lshlrev_b64 v[16:17], 12, v[16:17]
	v_lshl_add_u64 v[16:17], s[40:41], 0, v[16:17]
	v_lshl_add_u64 v[16:17], v[16:17], 0, v[184:185]
	v_mov_b32_e32 v151, v185
	v_lshl_add_u64 v[40:41], v[16:17], 0, v[150:151]
	v_add_u32_e32 v16, s28, v26
	v_ashrrev_i32_e32 v17, 31, v16
	v_lshlrev_b64 v[16:17], 11, v[16:17]
	v_lshl_add_u64 v[16:17], s[54:55], 0, v[16:17]
	v_mov_b32_e32 v189, v185
	v_lshl_add_u64 v[16:17], v[16:17], 0, v[188:189]
	v_mov_b32_e32 v149, v185
	v_lshl_add_u64 v[44:45], v[16:17], 0, v[148:149]
	global_load_dwordx4 v[16:19], v[186:187], off
	global_load_dwordx4 v[20:23], v[40:41], off
	global_load_dwordx2 v[48:49], v[44:45], off
	v_sub_u32_e32 v24, s30, v26
	v_ashrrev_i32_e32 v25, 31, v24
	v_lshlrev_b64 v[24:25], 11, v[24:25]
	v_lshl_add_u64 v[24:25], s[54:55], 0, v[24:25]
	v_lshl_add_u64 v[24:25], v[24:25], 0, v[188:189]
	v_lshl_add_u64 v[46:47], v[24:25], 0, v[148:149]
	v_mov_b32_e32 v64, 0
	v_cmp_lt_i32_e32 vcc, 0, v26
	v_pk_add_f32 v[14:15], v[14:15], v[144:145]
	v_pk_add_f32 v[50:51], v[12:13], v[146:147]
	v_mov_b32_e32 v13, 0
	v_mov_b32_e32 v12, 0
	global_load_dwordx2 v[74:75], v[46:47], off
	global_load_dwordx4 v[76:79], v[186:187], off offset:64
	global_load_dwordx4 v[32:35], v[40:41], off offset:64
	global_load_dwordx2 v[56:57], v[44:45], off offset:32
	global_load_dwordx2 v[80:81], v[46:47], off offset:32
	global_load_dwordx4 v[82:85], v[186:187], off offset:128
	global_load_dwordx4 v[86:89], v[40:41], off offset:128
	global_load_dwordx2 v[52:53], v[44:45], off offset:64
	global_load_dwordx2 v[90:91], v[46:47], off offset:64
	global_load_dwordx4 v[92:95], v[186:187], off offset:192
	global_load_dwordx4 v[96:99], v[40:41], off offset:192
	global_load_dwordx2 v[62:63], v[44:45], off offset:96
	global_load_dwordx2 v[100:101], v[46:47], off offset:96
	s_waitcnt vmcnt(0)
	s_and_saveexec_b64 s[0:1], vcc
	s_cbranch_execz .LBB0_910
	v_pk_add_f32 v[24:25], v[14:15], v[22:23]
	v_pk_add_f32 v[26:27], v[50:51], v[20:21]
	v_pk_fma_f32 v[24:25], v[24:25], s[18:19], v[18:19] op_sel_hi:[1,0,1]
	v_pk_fma_f32 v[26:27], v[26:27], s[18:19], v[16:17] op_sel_hi:[1,0,1]
	v_lshlrev_b32_e32 v28, 16, v74
	v_and_b32_e32 v29, 0xffff0000, v74
	v_lshlrev_b32_e32 v12, 16, v75
	v_and_b32_e32 v13, 0xffff0000, v75
	v_pk_mul_f32 v[26:27], v[26:27], v[28:29]
	v_pk_mul_f32 v[24:25], v[24:25], v[12:13]
	v_cvt_pk_bf16_f32 v12, v26, v27
	v_cvt_pk_bf16_f32 v13, v24, v25
.LBB0_910:
	s_or_b64 exec, exec, s[0:1]
	v_pk_add_f32 v[58:59], v[10:11], v[152:153]
	v_pk_add_f32 v[60:61], v[8:9], v[154:155]
	v_mov_b32_e32 v65, 0
	s_and_saveexec_b64 s[0:1], vcc
	s_cbranch_execz .LBB0_912
	v_pk_add_f32 v[10:11], v[58:59], v[34:35]
	v_pk_add_f32 v[24:25], v[60:61], v[32:33]
	v_pk_fma_f32 v[10:11], v[10:11], s[18:19], v[78:79] op_sel_hi:[1,0,1]
	v_pk_fma_f32 v[24:25], v[24:25], s[18:19], v[76:77] op_sel_hi:[1,0,1]
	v_lshlrev_b32_e32 v26, 16, v80
	v_and_b32_e32 v27, 0xffff0000, v80
	v_lshlrev_b32_e32 v8, 16, v81
	v_and_b32_e32 v9, 0xffff0000, v81
	v_pk_mul_f32 v[24:25], v[24:25], v[26:27]
	v_pk_mul_f32 v[8:9], v[10:11], v[8:9]
	v_cvt_pk_bf16_f32 v65, v24, v25
	v_cvt_pk_bf16_f32 v64, v8, v9
.LBB0_912:
	s_or_b64 exec, exec, s[0:1]
	v_pk_add_f32 v[6:7], v[6:7], v[158:159]
	v_pk_add_f32 v[54:55], v[4:5], v[160:161]
	v_mov_b32_e32 v66, 0
	v_mov_b32_e32 v5, 0
	v_mov_b32_e32 v4, 0
	s_and_saveexec_b64 s[0:1], vcc
	s_cbranch_execz .LBB0_914
	v_pk_add_f32 v[36:37], v[6:7], v[88:89]
	v_pk_add_f32 v[38:39], v[54:55], v[86:87]
	v_pk_fma_f32 v[36:37], v[36:37], s[18:19], v[84:85] op_sel_hi:[1,0,1]
	v_pk_fma_f32 v[38:39], v[38:39], s[18:19], v[82:83] op_sel_hi:[1,0,1]
	v_lshlrev_b32_e32 v42, 16, v90
	v_and_b32_e32 v43, 0xffff0000, v90
	v_lshlrev_b32_e32 v4, 16, v91
	v_and_b32_e32 v5, 0xffff0000, v91
	v_pk_mul_f32 v[38:39], v[38:39], v[42:43]
	v_pk_mul_f32 v[36:37], v[36:37], v[4:5]
	v_cvt_pk_bf16_f32 v4, v38, v39
	v_cvt_pk_bf16_f32 v5, v36, v37
; DEVI unsigned pk2(float lo, float hi) { f32x2 v = {lo, hi}; bf16x2_t b = __builtin_convertvector(v, bf16x2_t); return __builtin_bit_cast(unsigned, b); }
; DEVI float bflo(unsigned u) { return __uint_as_float(u << 16); }
; DEVI float bfhi(unsigned u) { return __uint_as_float(u & 0xffff0000u); }
;     template <int MT> DEVI void operator()(f32x4 (&acc)[MT][4], int row0, int col0, int fr, int fq) const {
;     ...
;                 o2[n].x = 0u; o2[n].y = 0u;
;                 if (k >= 1) {
;                     const uint2 s = *(const uint2*)(p2 + 16 * n);
;                     const f32x4 v = (yc + ys) * scale + bb;
;                     o2[n].x = pk2(v[0] * bflo(s.x), v[1] * bfhi(s.x)); o2[n].y = pk2(v[2] * bflo(s.y), v[3] * bfhi(s.y));
;                 }
;             }
;             const int wo = 16 * (fq & 1) + 8 * (fq >> 1) - 4 * fq;
; #pragma unroll
;             for (int n = 0; n < 4; n += 2) {
;                 const uint4 a1 = widen16(o1[n], o1[n + 1]), a2 = widen16(o2[n], o2[n + 1]);
;                 *(uint4*)(p1 + wo + 16 * n) = a1;
;                 if (k >= 1) *(uint4*)(p2 + wo + 16 * n) = a2;
;             }
.LBB0_914:
	s_or_b64 exec, exec, s[0:1]
	s_nop 0
	s_nop 0
	v_pk_add_f32 v[2:3], v[2:3], v[162:163]
	v_pk_add_f32 v[0:1], v[0:1], v[164:165]
	v_mov_b32_e32 v67, 0
	s_and_saveexec_b64 s[0:1], vcc
	s_cbranch_execz .LBB0_916
	v_pk_add_f32 v[68:69], v[2:3], v[98:99]
	v_pk_add_f32 v[70:71], v[0:1], v[96:97]
	v_pk_fma_f32 v[68:69], v[68:69], s[18:19], v[94:95] op_sel_hi:[1,0,1]
	v_pk_fma_f32 v[70:71], v[70:71], s[18:19], v[92:93] op_sel_hi:[1,0,1]
	v_lshlrev_b32_e32 v72, 16, v100
	v_and_b32_e32 v73, 0xffff0000, v100
	v_lshlrev_b32_e32 v66, 16, v101
	v_and_b32_e32 v67, 0xffff0000, v101
	v_pk_mul_f32 v[70:71], v[70:71], v[72:73]
	v_pk_mul_f32 v[68:69], v[68:69], v[66:67]
	v_cvt_pk_bf16_f32 v67, v70, v71
	v_cvt_pk_bf16_f32 v66, v68, v69
.LBB0_916:
	s_or_b64 exec, exec, s[0:1]
	v_sub_f32_e32 v33, v33, v61
	v_sub_f32_e32 v32, v32, v60
	v_sub_f32_e32 v35, v35, v59
	v_sub_f32_e32 v34, v34, v58
	v_pk_fma_f32 v[34:35], v[34:35], s[18:19], v[78:79] op_sel_hi:[1,0,1]
	v_pk_fma_f32 v[28:29], v[32:33], s[18:19], v[76:77] op_sel_hi:[1,0,1]
	v_lshlrev_b32_e32 v30, 16, v56
	v_and_b32_e32 v31, 0xffff0000, v56
	v_pk_mul_f32 v[28:29], v[28:29], v[30:31]
	v_sub_f32_e32 v21, v21, v51
	v_sub_f32_e32 v20, v20, v50
	v_sub_f32_e32 v15, v23, v15
	v_sub_f32_e32 v14, v22, v14
	v_cvt_pk_bf16_f32 v30, v28, v29
	v_lshlrev_b32_e32 v28, 16, v57
	v_and_b32_e32 v29, 0xffff0000, v57
	v_pk_fma_f32 v[14:15], v[14:15], s[18:19], v[18:19] op_sel_hi:[1,0,1]
	v_pk_fma_f32 v[16:17], v[20:21], s[18:19], v[16:17] op_sel_hi:[1,0,1]
	v_lshlrev_b32_e32 v18, 16, v48
	v_and_b32_e32 v19, 0xffff0000, v48
	v_pk_mul_f32 v[28:29], v[34:35], v[28:29]
	v_pk_mul_f32 v[16:17], v[16:17], v[18:19]
	v_cvt_pk_bf16_f32 v31, v28, v29
	v_cvt_pk_bf16_f32 v28, v16, v17
	v_lshlrev_b32_e32 v16, 16, v49
	v_and_b32_e32 v17, 0xffff0000, v49
	v_pk_mul_f32 v[14:15], v[14:15], v[16:17]
	v_lshl_add_u64 v[18:19], v[44:45], 0, v[156:157]
	v_cvt_pk_bf16_f32 v29, v14, v15
	v_lshl_add_u64 v[16:17], v[46:47], 0, v[156:157]
	v_permlane16_swap_b32_e32 v28, v30
	v_permlane16_swap_b32_e32 v29, v31
	v_permlane16_swap_b32_e32 v12, v65
	v_permlane16_swap_b32_e32 v13, v64
	global_store_dwordx4 v[18:19], v[28:31], off
	s_and_saveexec_b64 s[0:1], vcc
	s_cbranch_execz .LBB0_918
	v_mov_b32_e32 v14, v65
	v_mov_b32_e32 v15, v64
	global_store_dwordx4 v[16:17], v[12:15], off
.LBB0_918:
	s_or_b64 exec, exec, s[0:1]
	v_sub_f32_e32 v1, v97, v1
	v_sub_f32_e32 v0, v96, v0
	v_sub_f32_e32 v3, v99, v3
	v_sub_f32_e32 v2, v98, v2
	v_pk_fma_f32 v[12:13], v[2:3], s[18:19], v[94:95] op_sel_hi:[1,0,1]
	v_pk_fma_f32 v[0:1], v[0:1], s[18:19], v[92:93] op_sel_hi:[1,0,1]
	v_lshlrev_b32_e32 v2, 16, v62
	v_and_b32_e32 v3, 0xffff0000, v62
	v_pk_mul_f32 v[0:1], v[0:1], v[2:3]
	v_sub_f32_e32 v7, v89, v7
	v_cvt_pk_bf16_f32 v2, v0, v1
	v_lshlrev_b32_e32 v0, 16, v63
	v_and_b32_e32 v1, 0xffff0000, v63
	v_pk_mul_f32 v[0:1], v[12:13], v[0:1]
	v_sub_f32_e32 v6, v88, v6
	v_cvt_pk_bf16_f32 v3, v0, v1
	v_sub_f32_e32 v1, v87, v55
	v_sub_f32_e32 v0, v86, v54
	v_pk_fma_f32 v[0:1], v[0:1], s[18:19], v[82:83] op_sel_hi:[1,0,1]
	v_lshlrev_b32_e32 v8, 16, v52
	v_and_b32_e32 v9, 0xffff0000, v52
	v_pk_fma_f32 v[6:7], v[6:7], s[18:19], v[84:85] op_sel_hi:[1,0,1]
	v_pk_mul_f32 v[0:1], v[0:1], v[8:9]
	v_lshlrev_b32_e32 v8, 16, v53
	v_and_b32_e32 v9, 0xffff0000, v53
	v_pk_mul_f32 v[6:7], v[6:7], v[8:9]
	v_cvt_pk_bf16_f32 v0, v0, v1
	v_cvt_pk_bf16_f32 v1, v6, v7
	s_nop 0
	v_permlane16_swap_b32_e32 v0, v2
	v_permlane16_swap_b32_e32 v1, v3
	v_permlane16_swap_b32_e32 v4, v67
	v_permlane16_swap_b32_e32 v5, v66
	global_store_dwordx4 v[18:19], v[0:3], off offset:64
	s_and_saveexec_b64 s[0:1], vcc
	s_cbranch_execz .LBB0_815
	v_mov_b32_e32 v6, v67
	v_mov_b32_e32 v7, v66
	global_store_dwordx4 v[16:17], v[4:7], off offset:64
	s_branch .LBB0_815

; __global__ void __launch_bounds__(256, 2) fwd_megakernel(P p) {
	.amdhsa_kernel _Z14fwd_megakernel1P
		.amdhsa_group_segment_fixed_size 0
		.amdhsa_private_segment_fixed_size 0
		.amdhsa_kernarg_size 480
		.amdhsa_user_sgpr_count 2
		.amdhsa_user_sgpr_dispatch_ptr 0
		.amdhsa_user_sgpr_queue_ptr 0
		.amdhsa_user_sgpr_kernarg_segment_ptr 1
		.amdhsa_user_sgpr_dispatch_id 0
		.amdhsa_user_sgpr_kernarg_preload_length 0
		.amdhsa_user_sgpr_kernarg_preload_offset 0
		.amdhsa_user_sgpr_private_segment_size 0
		.amdhsa_uses_dynamic_stack 0
		.amdhsa_enable_private_segment 0
		.amdhsa_system_sgpr_workgroup_id_x 1
		.amdhsa_system_sgpr_workgroup_id_y 0
		.amdhsa_system_sgpr_workgroup_id_z 0
		.amdhsa_system_sgpr_workgroup_info 0
		.amdhsa_system_vgpr_workitem_id 2
		.amdhsa_next_free_vgpr 256
		.amdhsa_next_free_sgpr 102
		.amdhsa_accum_offset 256
		.amdhsa_reserve_vcc 1
		.amdhsa_float_round_mode_32 0
		.amdhsa_float_round_mode_16_64 0
		.amdhsa_float_denorm_mode_32 3
		.amdhsa_float_denorm_mode_16_64 3
		.amdhsa_dx10_clamp 1
		.amdhsa_ieee_mode 1
		.amdhsa_fp16_overflow 0
		.amdhsa_tg_split 0
		.amdhsa_exception_fp_ieee_invalid_op 0
		.amdhsa_exception_fp_denorm_src 0
		.amdhsa_exception_fp_ieee_div_zero 0
		.amdhsa_exception_fp_ieee_overflow 0
		.amdhsa_exception_fp_ieee_underflow 0
		.amdhsa_exception_fp_ieee_inexact 0
		.amdhsa_exception_int_div_zero 0
	.end_amdhsa_kernel

; __global__ void __launch_bounds__(256, 2) fwd_megakernel(P p) {
amdhsa.kernels:
  - .agpr_count:     0
    .args:
      - .offset:         0
        .size:           224
        .value_kind:     by_value
      - .offset:         224
        .size:           4
        .value_kind:     hidden_block_count_x
      - .offset:         228
        .size:           4
        .value_kind:     hidden_block_count_y
      - .offset:         232
        .size:           4
        .value_kind:     hidden_block_count_z
      - .offset:         236
        .size:           2
        .value_kind:     hidden_group_size_x
      - .offset:         238
        .size:           2
        .value_kind:     hidden_group_size_y
      - .offset:         240
        .size:           2
        .value_kind:     hidden_group_size_z
      - .offset:         242
        .size:           2
        .value_kind:     hidden_remainder_x
      - .offset:         244
        .size:           2
        .value_kind:     hidden_remainder_y
      - .offset:         246
        .size:           2
        .value_kind:     hidden_remainder_z
      - .offset:         264
        .size:           8
        .value_kind:     hidden_global_offset_x
      - .offset:         272
        .size:           8
        .value_kind:     hidden_global_offset_y
      - .offset:         280
        .size:           8
        .value_kind:     hidden_global_offset_z
      - .offset:         288
        .size:           2
        .value_kind:     hidden_grid_dims
      - .offset:         312
        .size:           8
        .value_kind:     hidden_multigrid_sync_arg
      - .offset:         344
        .size:           4
        .value_kind:     hidden_dynamic_lds_size
    .group_segment_fixed_size: 0
    .kernarg_segment_align: 8
    .kernarg_segment_size: 480
    .language:       OpenCL C
    .language_version:
      - 2
      - 0
    .max_flat_workgroup_size: 256
    .name:           _Z14fwd_megakernel1P
    .private_segment_fixed_size: 0
    .sgpr_count:     108
    .sgpr_spill_count: 46
    .symbol:         _Z14fwd_megakernel1P.kd
    .uniform_work_group_size: 1
    .uses_dynamic_stack: false
    .vgpr_count:     256
    .vgpr_spill_count: 0
    .wavefront_size: 64
